# attention loops: per-iteration address setup moved in front of the loop-back barrier (back-edge rotation)
# speedup vs baseline: 1.0128x; 1.0022x over previous
.LBB0_610:
	s_ashr_i32 s5, s23, 7
	s_bfe_u32 s4, s23, 0x20005
	s_mul_hi_i32 s8, s5, 0x3e00000
	s_mul_i32 s5, s5, 0x3e00000
	s_add_u32 s18, s2, s5
	s_addc_u32 s19, s17, s8
	s_lshl_b32 s5, s23, 7
	s_and_b32 s5, s5, 0xf80
	v_and_b32_e32 v64, 15, v2
	v_lshl_add_u32 v0, v3, 4, s5
	v_or_b32_e32 v66, v0, v64
	v_mov_b64_e32 v[20:21], s[18:19]
	v_mad_i64_i32 v[4:5], s[18:19], v66, s65, v[20:21]
	s_lshl_b32 s8, s4, 8
	v_bfe_u32 v65, v2, 4, 2
	v_lshl_add_u64 v[4:5], v[4:5], 0, s[8:9]
	s_mov_b64 s[18:19], 0x2200
	v_lshl_add_u64 v[132:133], v[4:5], 0, s[18:19]
	v_lshlrev_b32_e32 v0, 4, v65
	v_lshl_add_u64 v[16:17], v[132:133], 0, v[0:1]
	v_ashrrev_i32_e32 v67, 4, v2
	global_load_dwordx4 v[4:7], v[16:17], off
	global_load_dwordx4 v[8:11], v[16:17], off offset:64
	global_load_dwordx4 v[12:15], v[16:17], off offset:128
	s_nop 0
	global_load_dwordx4 v[16:19], v[16:17], off offset:192
	v_lshlrev_b32_e32 v0, 4, v2
	v_mad_i64_i32 v[20:21], s[18:19], v67, s65, v[20:21]
	v_lshl_add_u64 v[20:21], v[20:21], 0, s[8:9]
	v_and_b32_e32 v0, 0xf0, v0
	v_lshl_add_u64 v[36:37], v[20:21], 0, v[0:1]
	v_add_co_u32_e32 v24, vcc, s64, v36
	s_mov_b32 s5, 0x7e000
	s_nop 0
	v_addc_co_u32_e32 v25, vcc, 0, v37, vcc
	v_add_co_u32_e32 v32, vcc, s5, v36
	s_mov_b64 s[18:19], 0x2600
	s_waitcnt lgkmcnt(0)
	v_addc_co_u32_e32 v33, vcc, 0, v37, vcc
	global_load_dwordx4 v[20:23], v[24:25], off offset:1536
	s_nop 0
	global_load_dwordx4 v[24:27], v[24:25], off offset:2560
	s_nop 0
	global_load_dwordx4 v[28:31], v[32:33], off offset:1536
	s_nop 0
	global_load_dwordx4 v[32:35], v[32:33], off offset:2560
	v_lshl_add_u64 v[134:135], v[36:37], 0, s[18:19]
	s_mov_b64 s[18:19], 0x2a00
	v_lshl_add_u64 v[136:137], v[36:37], 0, s[18:19]
	v_mul_lo_u32 v36, v67, s21
	v_add3_u32 v169, 0, v0, v36
	v_lshlrev_b32_e32 v167, 2, v65
	s_barrier
	s_not_b32 s4, s4
	s_lshl_b32 s4, s4, 1
	v_ldexp_f32 v0, 1.0, s4
	v_lshlrev_b32_e32 v68, 3, v65
	v_mul_f32_e32 v150, 0x3fb8aa3b, v0
	v_readfirstlane_b32 s4, v3
	v_mul_u32_u24_e32 v0, 0x90, v64
	s_cmp_gt_i32 s4, 3
	s_mov_b64 s[4:5], -1
	v_lshlrev_b32_e32 v171, 1, v0
	v_lshlrev_b32_e32 v172, 1, v68
	s_waitcnt vmcnt(3)
	ds_write_b128 v169, v[20:23]
	s_waitcnt vmcnt(2)
	ds_write_b128 v169, v[24:27] offset:36864
	s_waitcnt vmcnt(1)
	ds_write_b128 v169, v[28:31] offset:9216
	s_waitcnt vmcnt(0)
	ds_write_b128 v169, v[32:35] offset:46080
	v_lshlrev_b32_e32 v38, 16, v4
	v_and_b32_e32 v39, 0xffff0000, v4
	v_lshlrev_b32_e32 v4, 16, v5
	v_and_b32_e32 v5, 0xffff0000, v5
	v_lshlrev_b32_e32 v50, 16, v16
	v_and_b32_e32 v51, 0xffff0000, v16
	v_pk_mul_f32 v[38:39], v[38:39], s[16:17] op_sel_hi:[1,0]
	v_pk_mul_f32 v[52:53], v[4:5], s[16:17] op_sel_hi:[1,0]
	v_cvt_pk_bf16_f32 v4, v38, v39
	v_pk_mul_f32 v[38:39], v[50:51], s[16:17] op_sel_hi:[1,0]
	v_sub_u32_e32 v20, v167, v66
	v_cvt_pk_bf16_f32 v16, v38, v39
	v_lshlrev_b32_e32 v38, 16, v17
	v_and_b32_e32 v39, 0xffff0000, v17
	v_pk_mul_f32 v[38:39], v[38:39], s[16:17] op_sel_hi:[1,0]
	v_cvt_f32_i32_e32 v170, v20
	v_cvt_pk_bf16_f32 v17, v38, v39
	v_lshlrev_b32_e32 v38, 16, v18
	v_and_b32_e32 v39, 0xffff0000, v18
	v_pk_mul_f32 v[38:39], v[38:39], s[16:17] op_sel_hi:[1,0]
	v_lshlrev_b32_e32 v40, 16, v6
	v_cvt_pk_bf16_f32 v18, v38, v39
	v_lshlrev_b32_e32 v38, 16, v19
	v_and_b32_e32 v39, 0xffff0000, v19
	v_pk_mul_f32 v[38:39], v[38:39], s[16:17] op_sel_hi:[1,0]
	v_and_b32_e32 v41, 0xffff0000, v6
	v_cvt_pk_bf16_f32 v19, v38, v39
	v_lshlrev_b32_e32 v38, 3, v2
	v_bfe_u32 v2, v2, 2, 2
	v_lshlrev_b32_e32 v6, 16, v7
	v_and_b32_e32 v7, 0xffff0000, v7
	v_lshlrev_b32_e32 v42, 16, v8
	v_and_b32_e32 v43, 0xffff0000, v8
	v_lshlrev_b32_e32 v8, 16, v9
	v_and_b32_e32 v9, 0xffff0000, v9
	v_lshlrev_b32_e32 v44, 16, v10
	v_and_b32_e32 v45, 0xffff0000, v10
	v_lshlrev_b32_e32 v10, 16, v11
	v_and_b32_e32 v11, 0xffff0000, v11
	v_lshlrev_b32_e32 v46, 16, v12
	v_and_b32_e32 v47, 0xffff0000, v12
	v_lshlrev_b32_e32 v12, 16, v13
	v_and_b32_e32 v13, 0xffff0000, v13
	v_lshlrev_b32_e32 v48, 16, v14
	v_and_b32_e32 v49, 0xffff0000, v14
	v_lshlrev_b32_e32 v14, 16, v15
	v_and_b32_e32 v15, 0xffff0000, v15
	v_or_b32_e32 v2, v167, v2
	v_pk_mul_f32 v[40:41], v[40:41], s[16:17] op_sel_hi:[1,0]
	v_pk_mul_f32 v[54:55], v[6:7], s[16:17] op_sel_hi:[1,0]
	v_pk_mul_f32 v[42:43], v[42:43], s[16:17] op_sel_hi:[1,0]
	v_pk_mul_f32 v[56:57], v[8:9], s[16:17] op_sel_hi:[1,0]
	v_pk_mul_f32 v[44:45], v[44:45], s[16:17] op_sel_hi:[1,0]
	v_pk_mul_f32 v[58:59], v[10:11], s[16:17] op_sel_hi:[1,0]
	v_pk_mul_f32 v[46:47], v[46:47], s[16:17] op_sel_hi:[1,0]
	v_pk_mul_f32 v[60:61], v[12:13], s[16:17] op_sel_hi:[1,0]
	v_pk_mul_f32 v[48:49], v[48:49], s[16:17] op_sel_hi:[1,0]
	v_pk_mul_f32 v[62:63], v[14:15], s[16:17] op_sel_hi:[1,0]
	v_and_b32_e32 v3, 24, v38
	v_mad_u32_u24 v2, v2, s21, 0
	v_cvt_pk_bf16_f32 v5, v52, v53
	v_cvt_pk_bf16_f32 v6, v40, v41
	v_cvt_pk_bf16_f32 v7, v54, v55
	v_cvt_pk_bf16_f32 v8, v42, v43
	v_cvt_pk_bf16_f32 v9, v56, v57
	v_cvt_pk_bf16_f32 v10, v44, v45
	v_cvt_pk_bf16_f32 v11, v58, v59
	v_cvt_pk_bf16_f32 v12, v46, v47
	v_cvt_pk_bf16_f32 v13, v60, v61
	v_cvt_pk_bf16_f32 v14, v48, v49
	v_cvt_pk_bf16_f32 v15, v62, v63
	v_add_u32_e32 v168, v2, v3
	s_waitcnt lgkmcnt(0)
	s_barrier
	s_cbranch_scc0 .Ld_groupA
	v_mov_b32_e32 v28, 0
	v_mov_b32_e32 v29, 0
	v_mov_b32_e32 v30, 0
	v_mov_b32_e32 v31, 0
	v_mov_b32_e32 v32, 0
	v_mov_b32_e32 v33, 0
	v_mov_b32_e32 v34, 0
	v_mov_b32_e32 v35, 0
	v_mov_b32_e32 v40, 0
	v_mov_b32_e32 v41, 0
	v_mov_b32_e32 v42, 0
	v_mov_b32_e32 v43, 0
	v_mov_b32_e32 v52, 0
	v_mov_b32_e32 v53, 0
	v_mov_b32_e32 v54, 0
	v_mov_b32_e32 v55, 0
	v_mov_b32_e32 v56, 0
	v_mov_b32_e32 v57, 0
	v_mov_b32_e32 v58, 0
	v_mov_b32_e32 v59, 0
	v_mov_b32_e32 v64, 0
	v_mov_b32_e32 v65, 0
	v_mov_b32_e32 v66, 0
	v_mov_b32_e32 v67, 0
	v_mov_b32_e32 v72, 0
	v_mov_b32_e32 v73, 0
	v_mov_b32_e32 v74, 0
	v_mov_b32_e32 v75, 0
	v_mov_b32_e32 v84, 0
	v_mov_b32_e32 v85, 0
	v_mov_b32_e32 v86, 0
	v_mov_b32_e32 v87, 0
	v_mov_b32_e32 v36, 0
	v_mov_b32_e32 v37, 0
	v_mov_b32_e32 v38, 0
	v_mov_b32_e32 v39, 0
	v_mov_b32_e32 v44, 0
	v_mov_b32_e32 v45, 0
	v_mov_b32_e32 v46, 0
	v_mov_b32_e32 v47, 0
	v_mov_b32_e32 v48, 0
	v_mov_b32_e32 v49, 0
	v_mov_b32_e32 v50, 0
	v_mov_b32_e32 v51, 0
	v_mov_b32_e32 v60, 0
	v_mov_b32_e32 v61, 0
	v_mov_b32_e32 v62, 0
	v_mov_b32_e32 v63, 0
	v_mov_b32_e32 v68, 0
	v_mov_b32_e32 v69, 0
	v_mov_b32_e32 v70, 0
	v_mov_b32_e32 v71, 0
	v_mov_b32_e32 v76, 0
	v_mov_b32_e32 v77, 0
	v_mov_b32_e32 v78, 0
	v_mov_b32_e32 v79, 0
	v_mov_b32_e32 v80, 0
	v_mov_b32_e32 v81, 0
	v_mov_b32_e32 v82, 0
	v_mov_b32_e32 v83, 0
	v_mov_b32_e32 v20, 0
	v_mov_b32_e32 v21, 0
	v_mov_b32_e32 v22, 0
	v_mov_b32_e32 v23, 0
	v_mov_b32_e32 v120, 0
	v_mov_b32_e32 v121, 0
	v_mov_b32_e32 v122, 0
	v_mov_b32_e32 v123, 0
	v_mov_b32_e32 v124, 0
	v_mov_b32_e32 v125, 0
	v_mov_b32_e32 v126, 0
	v_mov_b32_e32 v127, 0
	v_mov_b32_e32 v128, 0
	v_mov_b32_e32 v129, 0
	v_mov_b32_e32 v130, 0
	v_mov_b32_e32 v131, 0
	v_mov_b32_e32 v152, 0
	v_mov_b32_e32 v153, 0
	v_mov_b32_e32 v154, 0
	v_mov_b32_e32 v155, 0
	v_mov_b32_e32 v0, 0
	v_mov_b32_e32 v151, 0
	v_mov_b32_e32 v24, 0
	v_mov_b32_e32 v25, 0
	s_mov_b32 s66, 0xff800000
	v_add_u32_e32 v255, v171, v172
	v_mov_b32_e32 v165, v170
	v_readfirstlane_b32 s42, v134
	v_readfirstlane_b32 s43, v135
	v_readfirstlane_b32 s46, v136
	v_readfirstlane_b32 s47, v137
	s_nop 3
	v_subrev_u32_e32 v173, s42, v134
	v_subrev_u32_e32 v175, s46, v136
	s_mov_b32 s5, 0
	s_mov_b32 s31, 0
	s_mov_b32 s38, 0
	s_mov_b32 s39, 0x4800
	s_mov_b32 s30, 0xf8000
	v_add_u32_e32 v174, s31, v168
	v_add_u32_e32 v164, s39, v169
	s_add_u32 s80, s42, s30
	s_addc_u32 s81, s43, 0
	s_add_u32 s86, s80, 0x7c000
	s_addc_u32 s87, s81, 0
	s_add_u32 s96, s46, s30
	s_addc_u32 s97, s47, 0
	s_add_u32 s98, s96, 0x7c000
	s_addc_u32 s99, s97, 0
	v_mov_b32_e32 v88, 0xff800000
	v_mov_b32_e32 v89, 0xff800000
	v_mov_b32_e32 v90, 0xff800000
	v_mov_b32_e32 v91, 0xff800000
	v_mov_b32_e32 v92, 0xff800000
	v_mov_b32_e32 v93, 0xff800000
	v_mov_b32_e32 v94, 0xff800000
	v_mov_b32_e32 v95, 0xff800000
	v_mov_b32_e32 v96, 0xff800000
	v_mov_b32_e32 v97, 0xff800000
	v_mov_b32_e32 v98, 0xff800000
	v_mov_b32_e32 v99, 0xff800000
	v_mov_b32_e32 v100, 0xff800000
	v_mov_b32_e32 v101, 0xff800000
	v_mov_b32_e32 v102, 0xff800000
	v_mov_b32_e32 v103, 0xff800000
	v_mov_b32_e32 v104, 0xff800000
	v_mov_b32_e32 v105, 0xff800000
	v_mov_b32_e32 v106, 0xff800000
	v_mov_b32_e32 v107, 0xff800000
	v_mov_b32_e32 v108, 0xff800000
	v_mov_b32_e32 v109, 0xff800000
	v_mov_b32_e32 v110, 0xff800000
	v_mov_b32_e32 v111, 0xff800000
	v_mov_b32_e32 v112, 0xff800000
	v_mov_b32_e32 v113, 0xff800000
	v_mov_b32_e32 v114, 0xff800000
	v_mov_b32_e32 v115, 0xff800000
	v_mov_b32_e32 v116, 0xff800000
	v_mov_b32_e32 v117, 0xff800000
	v_mov_b32_e32 v118, 0xff800000
	v_mov_b32_e32 v119, 0xff800000
.Ld_loopB:
	global_load_dwordx4 v[212:215], v173, s[80:81]
	global_load_dwordx4 v[220:223], v175, s[96:97]
	global_load_dwordx4 v[216:219], v173, s[86:87]
	global_load_dwordx4 v[224:227], v175, s[98:99]
	ds_read_b128 v[228:231], v255 offset:0
	ds_read_b128 v[232:235], v255 offset:64
	ds_read_b128 v[236:239], v255 offset:4608
	ds_read_b128 v[240:243], v255 offset:4672
	v_max3_f32 v26, v88, v89, v90
	v_max3_f32 v26, v26, v91, v92
	v_max3_f32 v26, v26, v93, v94
	v_max3_f32 v26, v26, v95, v96
	v_max3_f32 v26, v26, v97, v98
	v_max3_f32 v26, v26, v99, v100
	v_max3_f32 v26, v26, v101, v102
	v_max_f32_e32 v26, v26, v103
	v_cmp_lt_f32_e32 vcc, s66, v26
	s_cbranch_vccz .Ld_nr_B0_0
	v_mov_b32_e32 v27, v26
	s_nop 1
	v_permlane16_swap_b32_e32 v26, v27
	v_max_f32_e32 v26, v26, v27
	v_mov_b32_e32 v27, v26
	s_nop 1
	v_permlane32_swap_b32_e32 v26, v27
	v_max_f32_e32 v26, v26, v27
	v_cmp_lt_f32_e32 vcc, s66, v26
	s_nop 1
	v_cndmask_b32_e32 v3, 0, v26, vcc
	v_sub_f32_e32 v2, 0, v3
	v_min_f32_e32 v2, 0, v2
	v_exp_f32_e32 v2, v2
	v_sub_f32_e32 v24, v24, v3
	v_mul_f32_e32 v0, v0, v2
	v_mul_f32_e32 v28, v28, v2
	v_mul_f32_e32 v29, v29, v2
	v_mul_f32_e32 v30, v30, v2
	v_mul_f32_e32 v31, v31, v2
	v_mul_f32_e32 v32, v32, v2
	v_mul_f32_e32 v33, v33, v2
	v_mul_f32_e32 v34, v34, v2
	v_mul_f32_e32 v35, v35, v2
	v_mul_f32_e32 v40, v40, v2
	v_mul_f32_e32 v41, v41, v2
	v_mul_f32_e32 v42, v42, v2
	v_mul_f32_e32 v43, v43, v2
	v_mul_f32_e32 v52, v52, v2
	v_mul_f32_e32 v53, v53, v2
	v_mul_f32_e32 v54, v54, v2
	v_mul_f32_e32 v55, v55, v2
	v_mul_f32_e32 v56, v56, v2
	v_mul_f32_e32 v57, v57, v2
	v_mul_f32_e32 v58, v58, v2
	v_mul_f32_e32 v59, v59, v2
	v_mul_f32_e32 v64, v64, v2
	v_mul_f32_e32 v65, v65, v2
	v_mul_f32_e32 v66, v66, v2
	v_mul_f32_e32 v67, v67, v2
	v_mul_f32_e32 v72, v72, v2
	v_mul_f32_e32 v73, v73, v2
	v_mul_f32_e32 v74, v74, v2
	v_mul_f32_e32 v75, v75, v2
	v_mul_f32_e32 v84, v84, v2
	v_mul_f32_e32 v85, v85, v2
	v_mul_f32_e32 v86, v86, v2
	v_mul_f32_e32 v87, v87, v2
	v_sub_f32_e32 v88, v88, v3
	v_sub_f32_e32 v89, v89, v3
	v_sub_f32_e32 v90, v90, v3
	v_sub_f32_e32 v91, v91, v3
	v_sub_f32_e32 v92, v92, v3
	v_sub_f32_e32 v93, v93, v3
	v_sub_f32_e32 v94, v94, v3
	v_sub_f32_e32 v95, v95, v3
	v_sub_f32_e32 v96, v96, v3
	v_sub_f32_e32 v97, v97, v3
	v_sub_f32_e32 v98, v98, v3
	v_sub_f32_e32 v99, v99, v3
	v_sub_f32_e32 v100, v100, v3
	v_sub_f32_e32 v101, v101, v3
	v_sub_f32_e32 v102, v102, v3
	v_sub_f32_e32 v103, v103, v3

.Ld_nr_B0_1:
	v_exp_f32_e32 v104, v104
	v_exp_f32_e32 v105, v105
	v_exp_f32_e32 v106, v106
	v_exp_f32_e32 v107, v107
	v_exp_f32_e32 v108, v108
	v_exp_f32_e32 v109, v109
	v_exp_f32_e32 v110, v110
	v_exp_f32_e32 v111, v111
	v_exp_f32_e32 v112, v112
	v_exp_f32_e32 v113, v113
	v_exp_f32_e32 v114, v114
	v_exp_f32_e32 v115, v115
	v_exp_f32_e32 v116, v116
	v_exp_f32_e32 v117, v117
	v_exp_f32_e32 v118, v118
	v_exp_f32_e32 v119, v119
	s_nop 0
	v_add_f32_e32 v26, v104, v105
	v_add_f32_e32 v26, v26, v106
	v_add_f32_e32 v26, v26, v107
	v_add_f32_e32 v26, v26, v108
	v_add_f32_e32 v26, v26, v109
	v_add_f32_e32 v26, v26, v110
	v_add_f32_e32 v26, v26, v111
	v_add_f32_e32 v26, v26, v112
	v_add_f32_e32 v26, v26, v113
	v_add_f32_e32 v26, v26, v114
	v_add_f32_e32 v26, v26, v115
	v_add_f32_e32 v26, v26, v116
	v_add_f32_e32 v26, v26, v117
	v_add_f32_e32 v26, v26, v118
	v_add_f32_e32 v26, v26, v119
	v_add_f32_e32 v151, v151, v26
	v_cvt_pk_bf16_f32 v128, v104, v105
	v_cvt_pk_bf16_f32 v129, v106, v107
	v_cvt_pk_bf16_f32 v130, v108, v109
	v_cvt_pk_bf16_f32 v131, v110, v111
	v_cvt_pk_bf16_f32 v152, v112, v113
	v_cvt_pk_bf16_f32 v153, v114, v115
	v_cvt_pk_bf16_f32 v154, v116, v117
	v_cvt_pk_bf16_f32 v155, v118, v119
	v_mov_b32_e32 v156, v165
	v_add_f32_e32 v157, 0x3f800000, v165
	v_add_f32_e32 v158, 0x40000000, v165
	v_add_f32_e32 v159, 0x40400000, v165
	v_add_f32_e32 v160, 0x41800000, v165
	v_add_f32_e32 v161, 0x41880000, v165
	v_add_f32_e32 v162, 0x41900000, v165
	v_add_f32_e32 v163, 0x41980000, v165
	v_add_f32_e32 v176, 0x42000000, v165
	v_add_f32_e32 v177, 0x42040000, v165
	v_add_f32_e32 v178, 0x42080000, v165
	v_add_f32_e32 v179, 0x420c0000, v165
	v_add_f32_e32 v180, 0x42400000, v165
	v_add_f32_e32 v181, 0x42440000, v165
	v_add_f32_e32 v182, 0x42480000, v165
	v_add_f32_e32 v183, 0x424c0000, v165
	v_fma_f32 v204, -v150, |v156|, v25
	v_fma_f32 v205, -v150, |v157|, v25
	v_fma_f32 v206, -v150, |v158|, v25
	v_fma_f32 v207, -v150, |v159|, v25
	v_fma_f32 v208, -v150, |v160|, v25
	v_fma_f32 v209, -v150, |v161|, v25
	v_fma_f32 v210, -v150, |v162|, v25
	v_fma_f32 v211, -v150, |v163|, v25
	v_fma_f32 v184, -v150, |v176|, v25
	v_fma_f32 v185, -v150, |v177|, v25
	v_fma_f32 v186, -v150, |v178|, v25
	v_fma_f32 v187, -v150, |v179|, v25
	v_fma_f32 v188, -v150, |v180|, v25
	v_fma_f32 v189, -v150, |v181|, v25
	v_fma_f32 v190, -v150, |v182|, v25
	v_fma_f32 v191, -v150, |v183|, v25
	v_fma_f32 v156, -v150, |v156|, v24
	v_fma_f32 v157, -v150, |v157|, v24
	v_fma_f32 v158, -v150, |v158|, v24
	v_fma_f32 v159, -v150, |v159|, v24
	v_fma_f32 v160, -v150, |v160|, v24
	v_fma_f32 v161, -v150, |v161|, v24
	v_fma_f32 v162, -v150, |v162|, v24
	v_fma_f32 v163, -v150, |v163|, v24
	v_fma_f32 v176, -v150, |v176|, v24
	v_fma_f32 v177, -v150, |v177|, v24
	v_fma_f32 v178, -v150, |v178|, v24
	v_fma_f32 v179, -v150, |v179|, v24
	v_fma_f32 v180, -v150, |v180|, v24
	v_fma_f32 v181, -v150, |v181|, v24
	v_fma_f32 v182, -v150, |v182|, v24
	v_fma_f32 v183, -v150, |v183|, v24
	ds_read_b128 v[244:247], v255 offset:9216
	s_waitcnt lgkmcnt(4)
	v_mfma_f32_16x16x32_bf16 v[88:91], v[228:231], v[4:7], v[156:159]
	ds_read_b128 v[248:251], v255 offset:9280
	s_waitcnt lgkmcnt(4)
	v_mfma_f32_16x16x32_bf16 v[88:91], v[232:235], v[8:11], v[88:91]
	ds_read_b128 v[228:231], v255 offset:13824
	s_waitcnt lgkmcnt(4)
	v_mfma_f32_16x16x32_bf16 v[92:95], v[236:239], v[4:7], v[160:163]
	ds_read_b128 v[232:235], v255 offset:13888
	s_waitcnt lgkmcnt(4)
	v_mfma_f32_16x16x32_bf16 v[92:95], v[240:243], v[8:11], v[92:95]
	ds_read_b128 v[236:239], v255 offset:128
	s_waitcnt lgkmcnt(4)
	v_mfma_f32_16x16x32_bf16 v[96:99], v[244:247], v[4:7], v[176:179]
	ds_read_b128 v[240:243], v255 offset:192
	s_waitcnt lgkmcnt(4)
	v_mfma_f32_16x16x32_bf16 v[96:99], v[248:251], v[8:11], v[96:99]
	ds_read_b128 v[244:247], v255 offset:4736
	s_waitcnt lgkmcnt(4)
	v_mfma_f32_16x16x32_bf16 v[100:103], v[228:231], v[4:7], v[180:183]
	ds_read_b128 v[248:251], v255 offset:4800
	s_waitcnt lgkmcnt(4)
	v_mfma_f32_16x16x32_bf16 v[100:103], v[232:235], v[8:11], v[100:103]
	ds_read_b128 v[228:231], v255 offset:9344
	s_waitcnt lgkmcnt(4)
	v_mfma_f32_16x16x32_bf16 v[104:107], v[236:239], v[12:15], v[204:207]
	ds_read_b128 v[232:235], v255 offset:9408
	s_waitcnt lgkmcnt(4)
	v_mfma_f32_16x16x32_bf16 v[104:107], v[240:243], v[16:19], v[104:107]
	ds_read_b128 v[236:239], v255 offset:13952
	s_waitcnt lgkmcnt(4)
	v_mfma_f32_16x16x32_bf16 v[108:111], v[244:247], v[12:15], v[208:211]
	ds_read_b128 v[240:243], v255 offset:14016
	s_waitcnt lgkmcnt(4)
	v_mfma_f32_16x16x32_bf16 v[108:111], v[248:251], v[16:19], v[108:111]
	ds_read_b64_tr_b16 v[244:245], v174 offset:36864
	ds_read_b64_tr_b16 v[246:247], v174 offset:41472
	s_waitcnt lgkmcnt(5)
	v_mfma_f32_16x16x32_bf16 v[112:115], v[228:231], v[12:15], v[184:187]
	ds_read_b64_tr_b16 v[248:249], v174 offset:36896
	ds_read_b64_tr_b16 v[250:251], v174 offset:41504
	s_waitcnt lgkmcnt(6)
	v_mfma_f32_16x16x32_bf16 v[112:115], v[232:235], v[16:19], v[112:115]
	ds_read_b64_tr_b16 v[228:229], v174 offset:36928
	ds_read_b64_tr_b16 v[230:231], v174 offset:41536
	s_waitcnt lgkmcnt(7)
	v_mfma_f32_16x16x32_bf16 v[116:119], v[236:239], v[12:15], v[188:191]
	ds_read_b64_tr_b16 v[232:233], v174 offset:36960
	ds_read_b64_tr_b16 v[234:235], v174 offset:41568
	s_waitcnt lgkmcnt(8)
	v_mfma_f32_16x16x32_bf16 v[116:119], v[240:243], v[16:19], v[116:119]
	ds_read_b64_tr_b16 v[236:237], v174 offset:36992
	ds_read_b64_tr_b16 v[238:239], v174 offset:41600
	s_waitcnt lgkmcnt(8)
	v_mfma_f32_16x16x32_bf16 v[28:31], v[244:247], v[120:123], v[28:31]
	v_mfma_f32_16x16x32_bf16 v[36:39], v[244:247], v[128:131], v[36:39]
	ds_read_b64_tr_b16 v[240:241], v174 offset:37024
	ds_read_b64_tr_b16 v[242:243], v174 offset:41632
	s_waitcnt lgkmcnt(8)
	v_mfma_f32_16x16x32_bf16 v[32:35], v[248:251], v[120:123], v[32:35]
	v_mfma_f32_16x16x32_bf16 v[44:47], v[248:251], v[128:131], v[44:47]
	ds_read_b64_tr_b16 v[244:245], v174 offset:37056
	ds_read_b64_tr_b16 v[246:247], v174 offset:41664
	s_waitcnt lgkmcnt(8)
	v_mfma_f32_16x16x32_bf16 v[40:43], v[228:231], v[120:123], v[40:43]
	v_mfma_f32_16x16x32_bf16 v[48:51], v[228:231], v[128:131], v[48:51]
	ds_read_b64_tr_b16 v[248:249], v174 offset:37088
	ds_read_b64_tr_b16 v[250:251], v174 offset:41696
	s_waitcnt lgkmcnt(8)
	v_mfma_f32_16x16x32_bf16 v[52:55], v[232:235], v[120:123], v[52:55]
	v_mfma_f32_16x16x32_bf16 v[60:63], v[232:235], v[128:131], v[60:63]
	ds_read_b64_tr_b16 v[228:229], v174 offset:46080
	ds_read_b64_tr_b16 v[230:231], v174 offset:50688
	s_waitcnt lgkmcnt(8)
	v_mfma_f32_16x16x32_bf16 v[56:59], v[236:239], v[120:123], v[56:59]
	v_mfma_f32_16x16x32_bf16 v[68:71], v[236:239], v[128:131], v[68:71]
	ds_read_b64_tr_b16 v[232:233], v174 offset:46112
	ds_read_b64_tr_b16 v[234:235], v174 offset:50720
	s_waitcnt lgkmcnt(8)
	v_mfma_f32_16x16x32_bf16 v[64:67], v[240:243], v[120:123], v[64:67]
	v_mfma_f32_16x16x32_bf16 v[76:79], v[240:243], v[128:131], v[76:79]
	ds_read_b64_tr_b16 v[236:237], v174 offset:46144
	ds_read_b64_tr_b16 v[238:239], v174 offset:50752
	s_waitcnt lgkmcnt(8)
	v_mfma_f32_16x16x32_bf16 v[72:75], v[244:247], v[120:123], v[72:75]
	v_mfma_f32_16x16x32_bf16 v[80:83], v[244:247], v[128:131], v[80:83]
	ds_read_b64_tr_b16 v[240:241], v174 offset:46176
	ds_read_b64_tr_b16 v[242:243], v174 offset:50784
	s_waitcnt lgkmcnt(8)
	v_mfma_f32_16x16x32_bf16 v[84:87], v[248:251], v[120:123], v[84:87]
	v_mfma_f32_16x16x32_bf16 v[20:23], v[248:251], v[128:131], v[20:23]
	ds_read_b64_tr_b16 v[244:245], v174 offset:46208
	ds_read_b64_tr_b16 v[246:247], v174 offset:50816
	s_waitcnt lgkmcnt(8)
	v_mfma_f32_16x16x32_bf16 v[28:31], v[228:231], v[124:127], v[28:31]
	v_mfma_f32_16x16x32_bf16 v[36:39], v[228:231], v[152:155], v[36:39]
	ds_read_b64_tr_b16 v[248:249], v174 offset:46240
	ds_read_b64_tr_b16 v[250:251], v174 offset:50848
	s_waitcnt lgkmcnt(8)
	v_mfma_f32_16x16x32_bf16 v[32:35], v[232:235], v[124:127], v[32:35]
	v_mfma_f32_16x16x32_bf16 v[44:47], v[232:235], v[152:155], v[44:47]
	ds_read_b64_tr_b16 v[228:229], v174 offset:46272
	ds_read_b64_tr_b16 v[230:231], v174 offset:50880
	s_waitcnt lgkmcnt(8)
	v_mfma_f32_16x16x32_bf16 v[40:43], v[236:239], v[124:127], v[40:43]
	v_mfma_f32_16x16x32_bf16 v[48:51], v[236:239], v[152:155], v[48:51]
	ds_read_b64_tr_b16 v[232:233], v174 offset:46304
	ds_read_b64_tr_b16 v[234:235], v174 offset:50912
	s_waitcnt lgkmcnt(8)
	v_mfma_f32_16x16x32_bf16 v[52:55], v[240:243], v[124:127], v[52:55]
	v_mfma_f32_16x16x32_bf16 v[60:63], v[240:243], v[152:155], v[60:63]
	s_waitcnt lgkmcnt(6)
	v_mfma_f32_16x16x32_bf16 v[56:59], v[244:247], v[124:127], v[56:59]
	v_mfma_f32_16x16x32_bf16 v[68:71], v[244:247], v[152:155], v[68:71]
	s_waitcnt lgkmcnt(4)
	v_mfma_f32_16x16x32_bf16 v[64:67], v[248:251], v[124:127], v[64:67]
	v_mfma_f32_16x16x32_bf16 v[76:79], v[248:251], v[152:155], v[76:79]
	s_waitcnt lgkmcnt(2)
	v_mfma_f32_16x16x32_bf16 v[72:75], v[228:231], v[124:127], v[72:75]
	v_mfma_f32_16x16x32_bf16 v[80:83], v[228:231], v[152:155], v[80:83]
	s_waitcnt lgkmcnt(0)
	v_mfma_f32_16x16x32_bf16 v[84:87], v[232:235], v[124:127], v[84:87]
	v_mfma_f32_16x16x32_bf16 v[20:23], v[232:235], v[152:155], v[20:23]
	s_waitcnt vmcnt(0)
	ds_write_b128 v169, v[212:215] offset:18432
	ds_write_b128 v169, v[216:219] offset:27648
	ds_write_b128 v164, v[220:223] offset:36864
	ds_write_b128 v164, v[224:227] offset:46080
	s_mov_b32 s31, s38
	s_mov_b32 s38, s39
	s_add_i32 s39, s39, 0x4800
	s_cmp_lg_u32 s39, 0xd800
	s_cselect_b32 s39, s39, 0
	s_mov_b32 s66, 0xff800000
	s_cmp_ge_u32 s5, 1
	s_cselect_b32 s66, 0x42800000, s66
	s_add_i32 s5, s5, 1
	s_min_u32 s8, s5, 62
	s_add_i32 s8, s8, 1
	s_mul_i32 s30, s8, 0xf8000
	v_add_f32_e32 v165, 0x42800000, v165
	v_add_u32_e32 v174, s31, v168
	v_add_u32_e32 v164, s39, v169
	s_add_u32 s80, s42, s30
	s_addc_u32 s81, s43, 0
	s_add_u32 s86, s80, 0x7c000
	s_addc_u32 s87, s81, 0
	s_add_u32 s96, s46, s30
	s_addc_u32 s97, s47, 0
	s_add_u32 s98, s96, 0x7c000
	s_addc_u32 s99, s97, 0
	s_waitcnt lgkmcnt(0)
	s_barrier
	global_load_dwordx4 v[212:215], v173, s[80:81]
	global_load_dwordx4 v[220:223], v175, s[96:97]
	global_load_dwordx4 v[216:219], v173, s[86:87]
	global_load_dwordx4 v[224:227], v175, s[98:99]
	ds_read_b128 v[228:231], v255 offset:18432
	ds_read_b128 v[232:235], v255 offset:18496
	ds_read_b128 v[236:239], v255 offset:23040
	ds_read_b128 v[240:243], v255 offset:23104
	v_max3_f32 v26, v88, v89, v90
	v_max3_f32 v26, v26, v91, v92
	v_max3_f32 v26, v26, v93, v94
	v_max3_f32 v26, v26, v95, v96
	v_max3_f32 v26, v26, v97, v98
	v_max3_f32 v26, v26, v99, v100
	v_max3_f32 v26, v26, v101, v102
	v_max_f32_e32 v26, v26, v103
	v_cmp_lt_f32_e32 vcc, s66, v26
	s_cbranch_vccz .Ld_nr_B1_0
	v_mov_b32_e32 v27, v26
	s_nop 1
	v_permlane16_swap_b32_e32 v26, v27
	v_max_f32_e32 v26, v26, v27
	v_mov_b32_e32 v27, v26
	s_nop 1
	v_permlane32_swap_b32_e32 v26, v27
	v_max_f32_e32 v26, v26, v27
	v_cmp_lt_f32_e32 vcc, s66, v26
	s_nop 1
	v_cndmask_b32_e32 v3, 0, v26, vcc
	v_sub_f32_e32 v2, 0, v3
	v_min_f32_e32 v2, 0, v2
	v_exp_f32_e32 v2, v2
	v_sub_f32_e32 v24, v24, v3
	v_mul_f32_e32 v0, v0, v2
	v_mul_f32_e32 v28, v28, v2
	v_mul_f32_e32 v29, v29, v2
	v_mul_f32_e32 v30, v30, v2
	v_mul_f32_e32 v31, v31, v2
	v_mul_f32_e32 v32, v32, v2
	v_mul_f32_e32 v33, v33, v2
	v_mul_f32_e32 v34, v34, v2
	v_mul_f32_e32 v35, v35, v2
	v_mul_f32_e32 v40, v40, v2
	v_mul_f32_e32 v41, v41, v2
	v_mul_f32_e32 v42, v42, v2
	v_mul_f32_e32 v43, v43, v2
	v_mul_f32_e32 v52, v52, v2
	v_mul_f32_e32 v53, v53, v2
	v_mul_f32_e32 v54, v54, v2
	v_mul_f32_e32 v55, v55, v2
	v_mul_f32_e32 v56, v56, v2
	v_mul_f32_e32 v57, v57, v2
	v_mul_f32_e32 v58, v58, v2
	v_mul_f32_e32 v59, v59, v2
	v_mul_f32_e32 v64, v64, v2
	v_mul_f32_e32 v65, v65, v2
	v_mul_f32_e32 v66, v66, v2
	v_mul_f32_e32 v67, v67, v2
	v_mul_f32_e32 v72, v72, v2
	v_mul_f32_e32 v73, v73, v2
	v_mul_f32_e32 v74, v74, v2
	v_mul_f32_e32 v75, v75, v2
	v_mul_f32_e32 v84, v84, v2
	v_mul_f32_e32 v85, v85, v2
	v_mul_f32_e32 v86, v86, v2
	v_mul_f32_e32 v87, v87, v2
	v_sub_f32_e32 v88, v88, v3
	v_sub_f32_e32 v89, v89, v3
	v_sub_f32_e32 v90, v90, v3
	v_sub_f32_e32 v91, v91, v3
	v_sub_f32_e32 v92, v92, v3
	v_sub_f32_e32 v93, v93, v3
	v_sub_f32_e32 v94, v94, v3
	v_sub_f32_e32 v95, v95, v3
	v_sub_f32_e32 v96, v96, v3
	v_sub_f32_e32 v97, v97, v3
	v_sub_f32_e32 v98, v98, v3
	v_sub_f32_e32 v99, v99, v3
	v_sub_f32_e32 v100, v100, v3
	v_sub_f32_e32 v101, v101, v3
	v_sub_f32_e32 v102, v102, v3
	v_sub_f32_e32 v103, v103, v3

.Ld_nr_B1_1:
	v_exp_f32_e32 v104, v104
	v_exp_f32_e32 v105, v105
	v_exp_f32_e32 v106, v106
	v_exp_f32_e32 v107, v107
	v_exp_f32_e32 v108, v108
	v_exp_f32_e32 v109, v109
	v_exp_f32_e32 v110, v110
	v_exp_f32_e32 v111, v111
	v_exp_f32_e32 v112, v112
	v_exp_f32_e32 v113, v113
	v_exp_f32_e32 v114, v114
	v_exp_f32_e32 v115, v115
	v_exp_f32_e32 v116, v116
	v_exp_f32_e32 v117, v117
	v_exp_f32_e32 v118, v118
	v_exp_f32_e32 v119, v119
	s_nop 0
	v_add_f32_e32 v26, v104, v105
	v_add_f32_e32 v26, v26, v106
	v_add_f32_e32 v26, v26, v107
	v_add_f32_e32 v26, v26, v108
	v_add_f32_e32 v26, v26, v109
	v_add_f32_e32 v26, v26, v110
	v_add_f32_e32 v26, v26, v111
	v_add_f32_e32 v26, v26, v112
	v_add_f32_e32 v26, v26, v113
	v_add_f32_e32 v26, v26, v114
	v_add_f32_e32 v26, v26, v115
	v_add_f32_e32 v26, v26, v116
	v_add_f32_e32 v26, v26, v117
	v_add_f32_e32 v26, v26, v118
	v_add_f32_e32 v26, v26, v119
	v_add_f32_e32 v151, v151, v26
	v_cvt_pk_bf16_f32 v128, v104, v105
	v_cvt_pk_bf16_f32 v129, v106, v107
	v_cvt_pk_bf16_f32 v130, v108, v109
	v_cvt_pk_bf16_f32 v131, v110, v111
	v_cvt_pk_bf16_f32 v152, v112, v113
	v_cvt_pk_bf16_f32 v153, v114, v115
	v_cvt_pk_bf16_f32 v154, v116, v117
	v_cvt_pk_bf16_f32 v155, v118, v119
	v_mov_b32_e32 v156, v165
	v_add_f32_e32 v157, 0x3f800000, v165
	v_add_f32_e32 v158, 0x40000000, v165
	v_add_f32_e32 v159, 0x40400000, v165
	v_add_f32_e32 v160, 0x41800000, v165
	v_add_f32_e32 v161, 0x41880000, v165
	v_add_f32_e32 v162, 0x41900000, v165
	v_add_f32_e32 v163, 0x41980000, v165
	v_add_f32_e32 v176, 0x42000000, v165
	v_add_f32_e32 v177, 0x42040000, v165
	v_add_f32_e32 v178, 0x42080000, v165
	v_add_f32_e32 v179, 0x420c0000, v165
	v_add_f32_e32 v180, 0x42400000, v165
	v_add_f32_e32 v181, 0x42440000, v165
	v_add_f32_e32 v182, 0x42480000, v165
	v_add_f32_e32 v183, 0x424c0000, v165
	v_fma_f32 v204, -v150, |v156|, v25
	v_fma_f32 v205, -v150, |v157|, v25
	v_fma_f32 v206, -v150, |v158|, v25
	v_fma_f32 v207, -v150, |v159|, v25
	v_fma_f32 v208, -v150, |v160|, v25
	v_fma_f32 v209, -v150, |v161|, v25
	v_fma_f32 v210, -v150, |v162|, v25
	v_fma_f32 v211, -v150, |v163|, v25
	v_fma_f32 v184, -v150, |v176|, v25
	v_fma_f32 v185, -v150, |v177|, v25
	v_fma_f32 v186, -v150, |v178|, v25
	v_fma_f32 v187, -v150, |v179|, v25
	v_fma_f32 v188, -v150, |v180|, v25
	v_fma_f32 v189, -v150, |v181|, v25
	v_fma_f32 v190, -v150, |v182|, v25
	v_fma_f32 v191, -v150, |v183|, v25
	v_fma_f32 v156, -v150, |v156|, v24
	v_fma_f32 v157, -v150, |v157|, v24
	v_fma_f32 v158, -v150, |v158|, v24
	v_fma_f32 v159, -v150, |v159|, v24
	v_fma_f32 v160, -v150, |v160|, v24
	v_fma_f32 v161, -v150, |v161|, v24
	v_fma_f32 v162, -v150, |v162|, v24
	v_fma_f32 v163, -v150, |v163|, v24
	v_fma_f32 v176, -v150, |v176|, v24
	v_fma_f32 v177, -v150, |v177|, v24
	v_fma_f32 v178, -v150, |v178|, v24
	v_fma_f32 v179, -v150, |v179|, v24
	v_fma_f32 v180, -v150, |v180|, v24
	v_fma_f32 v181, -v150, |v181|, v24
	v_fma_f32 v182, -v150, |v182|, v24
	v_fma_f32 v183, -v150, |v183|, v24
	ds_read_b128 v[244:247], v255 offset:27648
	s_waitcnt lgkmcnt(4)
	v_mfma_f32_16x16x32_bf16 v[88:91], v[228:231], v[4:7], v[156:159]
	ds_read_b128 v[248:251], v255 offset:27712
	s_waitcnt lgkmcnt(4)
	v_mfma_f32_16x16x32_bf16 v[88:91], v[232:235], v[8:11], v[88:91]
	ds_read_b128 v[228:231], v255 offset:32256
	s_waitcnt lgkmcnt(4)
	v_mfma_f32_16x16x32_bf16 v[92:95], v[236:239], v[4:7], v[160:163]
	ds_read_b128 v[232:235], v255 offset:32320
	s_waitcnt lgkmcnt(4)
	v_mfma_f32_16x16x32_bf16 v[92:95], v[240:243], v[8:11], v[92:95]
	ds_read_b128 v[236:239], v255 offset:18560
	s_waitcnt lgkmcnt(4)
	v_mfma_f32_16x16x32_bf16 v[96:99], v[244:247], v[4:7], v[176:179]
	ds_read_b128 v[240:243], v255 offset:18624
	s_waitcnt lgkmcnt(4)
	v_mfma_f32_16x16x32_bf16 v[96:99], v[248:251], v[8:11], v[96:99]
	ds_read_b128 v[244:247], v255 offset:23168
	s_waitcnt lgkmcnt(4)
	v_mfma_f32_16x16x32_bf16 v[100:103], v[228:231], v[4:7], v[180:183]
	ds_read_b128 v[248:251], v255 offset:23232
	s_waitcnt lgkmcnt(4)
	v_mfma_f32_16x16x32_bf16 v[100:103], v[232:235], v[8:11], v[100:103]
	ds_read_b128 v[228:231], v255 offset:27776
	s_waitcnt lgkmcnt(4)
	v_mfma_f32_16x16x32_bf16 v[104:107], v[236:239], v[12:15], v[204:207]
	ds_read_b128 v[232:235], v255 offset:27840
	s_waitcnt lgkmcnt(4)
	v_mfma_f32_16x16x32_bf16 v[104:107], v[240:243], v[16:19], v[104:107]
	ds_read_b128 v[236:239], v255 offset:32384
	s_waitcnt lgkmcnt(4)
	v_mfma_f32_16x16x32_bf16 v[108:111], v[244:247], v[12:15], v[208:211]
	ds_read_b128 v[240:243], v255 offset:32448
	s_waitcnt lgkmcnt(4)
	v_mfma_f32_16x16x32_bf16 v[108:111], v[248:251], v[16:19], v[108:111]
	ds_read_b64_tr_b16 v[244:245], v174 offset:36864
	ds_read_b64_tr_b16 v[246:247], v174 offset:41472
	s_waitcnt lgkmcnt(5)
	v_mfma_f32_16x16x32_bf16 v[112:115], v[228:231], v[12:15], v[184:187]
	ds_read_b64_tr_b16 v[248:249], v174 offset:36896
	ds_read_b64_tr_b16 v[250:251], v174 offset:41504
	s_waitcnt lgkmcnt(6)
	v_mfma_f32_16x16x32_bf16 v[112:115], v[232:235], v[16:19], v[112:115]
	ds_read_b64_tr_b16 v[228:229], v174 offset:36928
	ds_read_b64_tr_b16 v[230:231], v174 offset:41536
	s_waitcnt lgkmcnt(7)
	v_mfma_f32_16x16x32_bf16 v[116:119], v[236:239], v[12:15], v[188:191]
	ds_read_b64_tr_b16 v[232:233], v174 offset:36960
	ds_read_b64_tr_b16 v[234:235], v174 offset:41568
	s_waitcnt lgkmcnt(8)
	v_mfma_f32_16x16x32_bf16 v[116:119], v[240:243], v[16:19], v[116:119]
	ds_read_b64_tr_b16 v[236:237], v174 offset:36992
	ds_read_b64_tr_b16 v[238:239], v174 offset:41600
	s_waitcnt lgkmcnt(8)
	v_mfma_f32_16x16x32_bf16 v[28:31], v[244:247], v[120:123], v[28:31]
	v_mfma_f32_16x16x32_bf16 v[36:39], v[244:247], v[128:131], v[36:39]
	ds_read_b64_tr_b16 v[240:241], v174 offset:37024
	ds_read_b64_tr_b16 v[242:243], v174 offset:41632
	s_waitcnt lgkmcnt(8)
	v_mfma_f32_16x16x32_bf16 v[32:35], v[248:251], v[120:123], v[32:35]
	v_mfma_f32_16x16x32_bf16 v[44:47], v[248:251], v[128:131], v[44:47]
	ds_read_b64_tr_b16 v[244:245], v174 offset:37056
	ds_read_b64_tr_b16 v[246:247], v174 offset:41664
	s_waitcnt lgkmcnt(8)
	v_mfma_f32_16x16x32_bf16 v[40:43], v[228:231], v[120:123], v[40:43]
	v_mfma_f32_16x16x32_bf16 v[48:51], v[228:231], v[128:131], v[48:51]
	ds_read_b64_tr_b16 v[248:249], v174 offset:37088
	ds_read_b64_tr_b16 v[250:251], v174 offset:41696
	s_waitcnt lgkmcnt(8)
	v_mfma_f32_16x16x32_bf16 v[52:55], v[232:235], v[120:123], v[52:55]
	v_mfma_f32_16x16x32_bf16 v[60:63], v[232:235], v[128:131], v[60:63]
	ds_read_b64_tr_b16 v[228:229], v174 offset:46080
	ds_read_b64_tr_b16 v[230:231], v174 offset:50688
	s_waitcnt lgkmcnt(8)
	v_mfma_f32_16x16x32_bf16 v[56:59], v[236:239], v[120:123], v[56:59]
	v_mfma_f32_16x16x32_bf16 v[68:71], v[236:239], v[128:131], v[68:71]
	ds_read_b64_tr_b16 v[232:233], v174 offset:46112
	ds_read_b64_tr_b16 v[234:235], v174 offset:50720
	s_waitcnt lgkmcnt(8)
	v_mfma_f32_16x16x32_bf16 v[64:67], v[240:243], v[120:123], v[64:67]
	v_mfma_f32_16x16x32_bf16 v[76:79], v[240:243], v[128:131], v[76:79]
	ds_read_b64_tr_b16 v[236:237], v174 offset:46144
	ds_read_b64_tr_b16 v[238:239], v174 offset:50752
	s_waitcnt lgkmcnt(8)
	v_mfma_f32_16x16x32_bf16 v[72:75], v[244:247], v[120:123], v[72:75]
	v_mfma_f32_16x16x32_bf16 v[80:83], v[244:247], v[128:131], v[80:83]
	ds_read_b64_tr_b16 v[240:241], v174 offset:46176
	ds_read_b64_tr_b16 v[242:243], v174 offset:50784
	s_waitcnt lgkmcnt(8)
	v_mfma_f32_16x16x32_bf16 v[84:87], v[248:251], v[120:123], v[84:87]
	v_mfma_f32_16x16x32_bf16 v[20:23], v[248:251], v[128:131], v[20:23]
	ds_read_b64_tr_b16 v[244:245], v174 offset:46208
	ds_read_b64_tr_b16 v[246:247], v174 offset:50816
	s_waitcnt lgkmcnt(8)
	v_mfma_f32_16x16x32_bf16 v[28:31], v[228:231], v[124:127], v[28:31]
	v_mfma_f32_16x16x32_bf16 v[36:39], v[228:231], v[152:155], v[36:39]
	ds_read_b64_tr_b16 v[248:249], v174 offset:46240
	ds_read_b64_tr_b16 v[250:251], v174 offset:50848
	s_waitcnt lgkmcnt(8)
	v_mfma_f32_16x16x32_bf16 v[32:35], v[232:235], v[124:127], v[32:35]
	v_mfma_f32_16x16x32_bf16 v[44:47], v[232:235], v[152:155], v[44:47]
	ds_read_b64_tr_b16 v[228:229], v174 offset:46272
	ds_read_b64_tr_b16 v[230:231], v174 offset:50880
	s_waitcnt lgkmcnt(8)
	v_mfma_f32_16x16x32_bf16 v[40:43], v[236:239], v[124:127], v[40:43]
	v_mfma_f32_16x16x32_bf16 v[48:51], v[236:239], v[152:155], v[48:51]
	ds_read_b64_tr_b16 v[232:233], v174 offset:46304
	ds_read_b64_tr_b16 v[234:235], v174 offset:50912
	s_waitcnt lgkmcnt(8)
	v_mfma_f32_16x16x32_bf16 v[52:55], v[240:243], v[124:127], v[52:55]
	v_mfma_f32_16x16x32_bf16 v[60:63], v[240:243], v[152:155], v[60:63]
	s_waitcnt lgkmcnt(6)
	v_mfma_f32_16x16x32_bf16 v[56:59], v[244:247], v[124:127], v[56:59]
	v_mfma_f32_16x16x32_bf16 v[68:71], v[244:247], v[152:155], v[68:71]
	s_waitcnt lgkmcnt(4)
	v_mfma_f32_16x16x32_bf16 v[64:67], v[248:251], v[124:127], v[64:67]
	v_mfma_f32_16x16x32_bf16 v[76:79], v[248:251], v[152:155], v[76:79]
	s_waitcnt lgkmcnt(2)
	v_mfma_f32_16x16x32_bf16 v[72:75], v[228:231], v[124:127], v[72:75]
	v_mfma_f32_16x16x32_bf16 v[80:83], v[228:231], v[152:155], v[80:83]
	s_waitcnt lgkmcnt(0)
	v_mfma_f32_16x16x32_bf16 v[84:87], v[232:235], v[124:127], v[84:87]
	v_mfma_f32_16x16x32_bf16 v[20:23], v[232:235], v[152:155], v[20:23]
	s_waitcnt vmcnt(0)
	ds_write_b128 v169, v[212:215] offset:0
	ds_write_b128 v169, v[216:219] offset:9216
	ds_write_b128 v164, v[220:223] offset:36864
	ds_write_b128 v164, v[224:227] offset:46080
	s_mov_b32 s31, s38
	s_mov_b32 s38, s39
	s_add_i32 s39, s39, 0x4800
	s_cmp_lg_u32 s39, 0xd800
	s_cselect_b32 s39, s39, 0
	s_mov_b32 s66, 0xff800000
	s_cmp_ge_u32 s5, 1
	s_cselect_b32 s66, 0x42800000, s66
	s_add_i32 s5, s5, 1
	s_min_u32 s8, s5, 62
	s_add_i32 s8, s8, 1
	s_mul_i32 s30, s8, 0xf8000
	v_add_f32_e32 v165, 0x42800000, v165
	v_add_u32_e32 v174, s31, v168
	v_add_u32_e32 v164, s39, v169
	s_add_u32 s80, s42, s30
	s_addc_u32 s81, s43, 0
	s_add_u32 s86, s80, 0x7c000
	s_addc_u32 s87, s81, 0
	s_add_u32 s96, s46, s30
	s_addc_u32 s97, s47, 0
	s_add_u32 s98, s96, 0x7c000
	s_addc_u32 s99, s97, 0
	s_waitcnt lgkmcnt(0)
	s_barrier
	s_cmp_lt_u32 s5, 64
	s_cbranch_scc1 .Ld_loopB
	v_add_u32_e32 v174, s31, v168
	ds_read_b64_tr_b16 v[228:229], v174 offset:36864
	ds_read_b64_tr_b16 v[230:231], v174 offset:41472
	ds_read_b64_tr_b16 v[232:233], v174 offset:36896
	ds_read_b64_tr_b16 v[234:235], v174 offset:41504
	ds_read_b64_tr_b16 v[236:237], v174 offset:36928
	ds_read_b64_tr_b16 v[238:239], v174 offset:41536
	ds_read_b64_tr_b16 v[240:241], v174 offset:36960
	ds_read_b64_tr_b16 v[242:243], v174 offset:41568
	v_max3_f32 v26, v88, v89, v90
	v_max3_f32 v26, v26, v91, v92
	v_max3_f32 v26, v26, v93, v94
	v_max3_f32 v26, v26, v95, v96
	v_max3_f32 v26, v26, v97, v98
	v_max3_f32 v26, v26, v99, v100
	v_max3_f32 v26, v26, v101, v102
	v_max_f32_e32 v26, v26, v103
	v_cmp_lt_f32_e32 vcc, s66, v26
	s_cbranch_vccz .Ld_nr_Bt_0
	v_mov_b32_e32 v27, v26
	s_nop 1
	v_permlane16_swap_b32_e32 v26, v27
	v_max_f32_e32 v26, v26, v27
	v_mov_b32_e32 v27, v26
	s_nop 1
	v_permlane32_swap_b32_e32 v26, v27
	v_max_f32_e32 v26, v26, v27
	v_cmp_lt_f32_e32 vcc, s66, v26
	s_nop 1
	v_cndmask_b32_e32 v3, 0, v26, vcc
	v_sub_f32_e32 v2, 0, v3
	v_min_f32_e32 v2, 0, v2
	v_exp_f32_e32 v2, v2
	v_sub_f32_e32 v24, v24, v3
	v_mul_f32_e32 v0, v0, v2
	v_mul_f32_e32 v28, v28, v2
	v_mul_f32_e32 v29, v29, v2
	v_mul_f32_e32 v30, v30, v2
	v_mul_f32_e32 v31, v31, v2
	v_mul_f32_e32 v32, v32, v2
	v_mul_f32_e32 v33, v33, v2
	v_mul_f32_e32 v34, v34, v2
	v_mul_f32_e32 v35, v35, v2
	v_mul_f32_e32 v40, v40, v2
	v_mul_f32_e32 v41, v41, v2
	v_mul_f32_e32 v42, v42, v2
	v_mul_f32_e32 v43, v43, v2
	v_mul_f32_e32 v52, v52, v2
	v_mul_f32_e32 v53, v53, v2
	v_mul_f32_e32 v54, v54, v2
	v_mul_f32_e32 v55, v55, v2
	v_mul_f32_e32 v56, v56, v2
	v_mul_f32_e32 v57, v57, v2
	v_mul_f32_e32 v58, v58, v2
	v_mul_f32_e32 v59, v59, v2
	v_mul_f32_e32 v64, v64, v2
	v_mul_f32_e32 v65, v65, v2
	v_mul_f32_e32 v66, v66, v2
	v_mul_f32_e32 v67, v67, v2
	v_mul_f32_e32 v72, v72, v2
	v_mul_f32_e32 v73, v73, v2
	v_mul_f32_e32 v74, v74, v2
	v_mul_f32_e32 v75, v75, v2
	v_mul_f32_e32 v84, v84, v2
	v_mul_f32_e32 v85, v85, v2
	v_mul_f32_e32 v86, v86, v2
	v_mul_f32_e32 v87, v87, v2
	v_sub_f32_e32 v88, v88, v3
	v_sub_f32_e32 v89, v89, v3
	v_sub_f32_e32 v90, v90, v3
	v_sub_f32_e32 v91, v91, v3
	v_sub_f32_e32 v92, v92, v3
	v_sub_f32_e32 v93, v93, v3
	v_sub_f32_e32 v94, v94, v3
	v_sub_f32_e32 v95, v95, v3
	v_sub_f32_e32 v96, v96, v3
	v_sub_f32_e32 v97, v97, v3
	v_sub_f32_e32 v98, v98, v3
	v_sub_f32_e32 v99, v99, v3
	v_sub_f32_e32 v100, v100, v3
	v_sub_f32_e32 v101, v101, v3
	v_sub_f32_e32 v102, v102, v3
	v_sub_f32_e32 v103, v103, v3

.Ld_groupA:
	v_mov_b32_e32 v28, 0
	v_mov_b32_e32 v29, 0
	v_mov_b32_e32 v30, 0
	v_mov_b32_e32 v31, 0
	v_mov_b32_e32 v32, 0
	v_mov_b32_e32 v33, 0
	v_mov_b32_e32 v34, 0
	v_mov_b32_e32 v35, 0
	v_mov_b32_e32 v40, 0
	v_mov_b32_e32 v41, 0
	v_mov_b32_e32 v42, 0
	v_mov_b32_e32 v43, 0
	v_mov_b32_e32 v52, 0
	v_mov_b32_e32 v53, 0
	v_mov_b32_e32 v54, 0
	v_mov_b32_e32 v55, 0
	v_mov_b32_e32 v56, 0
	v_mov_b32_e32 v57, 0
	v_mov_b32_e32 v58, 0
	v_mov_b32_e32 v59, 0
	v_mov_b32_e32 v64, 0
	v_mov_b32_e32 v65, 0
	v_mov_b32_e32 v66, 0
	v_mov_b32_e32 v67, 0
	v_mov_b32_e32 v72, 0
	v_mov_b32_e32 v73, 0
	v_mov_b32_e32 v74, 0
	v_mov_b32_e32 v75, 0
	v_mov_b32_e32 v84, 0
	v_mov_b32_e32 v85, 0
	v_mov_b32_e32 v86, 0
	v_mov_b32_e32 v87, 0
	v_mov_b32_e32 v36, 0
	v_mov_b32_e32 v37, 0
	v_mov_b32_e32 v38, 0
	v_mov_b32_e32 v39, 0
	v_mov_b32_e32 v44, 0
	v_mov_b32_e32 v45, 0
	v_mov_b32_e32 v46, 0
	v_mov_b32_e32 v47, 0
	v_mov_b32_e32 v48, 0
	v_mov_b32_e32 v49, 0
	v_mov_b32_e32 v50, 0
	v_mov_b32_e32 v51, 0
	v_mov_b32_e32 v60, 0
	v_mov_b32_e32 v61, 0
	v_mov_b32_e32 v62, 0
	v_mov_b32_e32 v63, 0
	v_mov_b32_e32 v68, 0
	v_mov_b32_e32 v69, 0
	v_mov_b32_e32 v70, 0
	v_mov_b32_e32 v71, 0
	v_mov_b32_e32 v76, 0
	v_mov_b32_e32 v77, 0
	v_mov_b32_e32 v78, 0
	v_mov_b32_e32 v79, 0
	v_mov_b32_e32 v80, 0
	v_mov_b32_e32 v81, 0
	v_mov_b32_e32 v82, 0
	v_mov_b32_e32 v83, 0
	v_mov_b32_e32 v20, 0
	v_mov_b32_e32 v21, 0
	v_mov_b32_e32 v22, 0
	v_mov_b32_e32 v23, 0
	v_mov_b32_e32 v120, 0
	v_mov_b32_e32 v121, 0
	v_mov_b32_e32 v122, 0
	v_mov_b32_e32 v123, 0
	v_mov_b32_e32 v124, 0
	v_mov_b32_e32 v125, 0
	v_mov_b32_e32 v126, 0
	v_mov_b32_e32 v127, 0
	v_mov_b32_e32 v128, 0
	v_mov_b32_e32 v129, 0
	v_mov_b32_e32 v130, 0
	v_mov_b32_e32 v131, 0
	v_mov_b32_e32 v152, 0
	v_mov_b32_e32 v153, 0
	v_mov_b32_e32 v154, 0
	v_mov_b32_e32 v155, 0
	v_mov_b32_e32 v0, 0
	v_mov_b32_e32 v151, 0
	v_mov_b32_e32 v24, 0
	v_mov_b32_e32 v25, 0
	s_mov_b32 s66, 0xff800000
	v_add_u32_e32 v255, v171, v172
	v_mov_b32_e32 v165, v170
	v_readfirstlane_b32 s42, v134
	v_readfirstlane_b32 s43, v135
	v_readfirstlane_b32 s46, v136
	v_readfirstlane_b32 s47, v137
	s_nop 3
	v_subrev_u32_e32 v173, s42, v134
	v_subrev_u32_e32 v175, s46, v136
	s_mov_b32 s5, 0
	s_mov_b32 s31, 0
	s_mov_b32 s38, 0
	s_mov_b32 s39, 0x4800
	s_mov_b32 s30, 0xf8000
	v_add_u32_e32 v174, s31, v168
	v_add_u32_e32 v164, s39, v169
	s_add_u32 s80, s42, s30
	s_addc_u32 s81, s43, 0
	s_add_u32 s86, s80, 0x7c000
	s_addc_u32 s87, s81, 0
	s_add_u32 s96, s46, s30
	s_addc_u32 s97, s47, 0
	s_add_u32 s98, s96, 0x7c000
	s_addc_u32 s99, s97, 0
	v_mov_b32_e32 v156, v165
	v_add_f32_e32 v157, 0x3f800000, v165
	v_add_f32_e32 v158, 0x40000000, v165
	v_add_f32_e32 v159, 0x40400000, v165
	v_add_f32_e32 v160, 0x41800000, v165
	v_add_f32_e32 v161, 0x41880000, v165
	v_add_f32_e32 v162, 0x41900000, v165
	v_add_f32_e32 v163, 0x41980000, v165
	v_add_f32_e32 v176, 0x42000000, v165
	v_add_f32_e32 v177, 0x42040000, v165
	v_add_f32_e32 v178, 0x42080000, v165
	v_add_f32_e32 v179, 0x420c0000, v165
	v_add_f32_e32 v180, 0x42400000, v165
	v_add_f32_e32 v181, 0x42440000, v165
	v_add_f32_e32 v182, 0x42480000, v165
	v_add_f32_e32 v183, 0x424c0000, v165
	v_fma_f32 v204, -v150, |v156|, v25
	v_fma_f32 v205, -v150, |v157|, v25
	v_fma_f32 v206, -v150, |v158|, v25
	v_fma_f32 v207, -v150, |v159|, v25
	v_fma_f32 v208, -v150, |v160|, v25
	v_fma_f32 v209, -v150, |v161|, v25
	v_fma_f32 v210, -v150, |v162|, v25
	v_fma_f32 v211, -v150, |v163|, v25
	v_fma_f32 v184, -v150, |v176|, v25
	v_fma_f32 v185, -v150, |v177|, v25
	v_fma_f32 v186, -v150, |v178|, v25
	v_fma_f32 v187, -v150, |v179|, v25
	v_fma_f32 v188, -v150, |v180|, v25
	v_fma_f32 v189, -v150, |v181|, v25
	v_fma_f32 v190, -v150, |v182|, v25
	v_fma_f32 v191, -v150, |v183|, v25
	v_fma_f32 v156, -v150, |v156|, v24
	v_fma_f32 v157, -v150, |v157|, v24
	v_fma_f32 v158, -v150, |v158|, v24
	v_fma_f32 v159, -v150, |v159|, v24
	v_fma_f32 v160, -v150, |v160|, v24
	v_fma_f32 v161, -v150, |v161|, v24
	v_fma_f32 v162, -v150, |v162|, v24
	v_fma_f32 v163, -v150, |v163|, v24
	v_fma_f32 v176, -v150, |v176|, v24
	v_fma_f32 v177, -v150, |v177|, v24
	v_fma_f32 v178, -v150, |v178|, v24
	v_fma_f32 v179, -v150, |v179|, v24
	v_fma_f32 v180, -v150, |v180|, v24
	v_fma_f32 v181, -v150, |v181|, v24
	v_fma_f32 v182, -v150, |v182|, v24
	v_fma_f32 v183, -v150, |v183|, v24
.Ld_loopA:
	global_load_dwordx4 v[212:215], v173, s[80:81]
	global_load_dwordx4 v[220:223], v175, s[96:97]
	global_load_dwordx4 v[216:219], v173, s[86:87]
	global_load_dwordx4 v[224:227], v175, s[98:99]
	ds_read_b64_tr_b16 v[228:229], v174 offset:36864
	ds_read_b64_tr_b16 v[230:231], v174 offset:41472
	ds_read_b64_tr_b16 v[232:233], v174 offset:36896
	ds_read_b64_tr_b16 v[234:235], v174 offset:41504
	ds_read_b64_tr_b16 v[236:237], v174 offset:36928
	ds_read_b64_tr_b16 v[238:239], v174 offset:41536
	ds_read_b64_tr_b16 v[240:241], v174 offset:36960
	ds_read_b64_tr_b16 v[242:243], v174 offset:41568
	ds_read_b64_tr_b16 v[244:245], v174 offset:36992
	ds_read_b64_tr_b16 v[246:247], v174 offset:41600
	s_waitcnt lgkmcnt(8)
	v_mfma_f32_16x16x32_bf16 v[28:31], v[228:231], v[120:123], v[28:31]
	v_mfma_f32_16x16x32_bf16 v[36:39], v[228:231], v[128:131], v[36:39]
	ds_read_b64_tr_b16 v[248:249], v174 offset:37024
	ds_read_b64_tr_b16 v[250:251], v174 offset:41632
	s_waitcnt lgkmcnt(8)
	v_mfma_f32_16x16x32_bf16 v[32:35], v[232:235], v[120:123], v[32:35]
	v_mfma_f32_16x16x32_bf16 v[44:47], v[232:235], v[128:131], v[44:47]
	ds_read_b64_tr_b16 v[228:229], v174 offset:37056
	ds_read_b64_tr_b16 v[230:231], v174 offset:41664
	s_waitcnt lgkmcnt(8)
	v_mfma_f32_16x16x32_bf16 v[40:43], v[236:239], v[120:123], v[40:43]
	v_mfma_f32_16x16x32_bf16 v[48:51], v[236:239], v[128:131], v[48:51]
	ds_read_b64_tr_b16 v[232:233], v174 offset:37088
	ds_read_b64_tr_b16 v[234:235], v174 offset:41696
	s_waitcnt lgkmcnt(8)
	v_mfma_f32_16x16x32_bf16 v[52:55], v[240:243], v[120:123], v[52:55]
	v_mfma_f32_16x16x32_bf16 v[60:63], v[240:243], v[128:131], v[60:63]
	ds_read_b64_tr_b16 v[236:237], v174 offset:46080
	ds_read_b64_tr_b16 v[238:239], v174 offset:50688
	s_waitcnt lgkmcnt(8)
	v_mfma_f32_16x16x32_bf16 v[56:59], v[244:247], v[120:123], v[56:59]
	v_mfma_f32_16x16x32_bf16 v[68:71], v[244:247], v[128:131], v[68:71]
	ds_read_b64_tr_b16 v[240:241], v174 offset:46112
	ds_read_b64_tr_b16 v[242:243], v174 offset:50720
	s_waitcnt lgkmcnt(8)
	v_mfma_f32_16x16x32_bf16 v[64:67], v[248:251], v[120:123], v[64:67]
	v_mfma_f32_16x16x32_bf16 v[76:79], v[248:251], v[128:131], v[76:79]
	ds_read_b64_tr_b16 v[244:245], v174 offset:46144
	ds_read_b64_tr_b16 v[246:247], v174 offset:50752
	s_waitcnt lgkmcnt(8)
	v_mfma_f32_16x16x32_bf16 v[72:75], v[228:231], v[120:123], v[72:75]
	v_mfma_f32_16x16x32_bf16 v[80:83], v[228:231], v[128:131], v[80:83]
	ds_read_b64_tr_b16 v[248:249], v174 offset:46176
	ds_read_b64_tr_b16 v[250:251], v174 offset:50784
	s_waitcnt lgkmcnt(8)
	v_mfma_f32_16x16x32_bf16 v[84:87], v[232:235], v[120:123], v[84:87]
	v_mfma_f32_16x16x32_bf16 v[20:23], v[232:235], v[128:131], v[20:23]
	ds_read_b64_tr_b16 v[228:229], v174 offset:46208
	ds_read_b64_tr_b16 v[230:231], v174 offset:50816
	s_waitcnt lgkmcnt(8)
	v_mfma_f32_16x16x32_bf16 v[28:31], v[236:239], v[124:127], v[28:31]
	v_mfma_f32_16x16x32_bf16 v[36:39], v[236:239], v[152:155], v[36:39]
	ds_read_b64_tr_b16 v[232:233], v174 offset:46240
	ds_read_b64_tr_b16 v[234:235], v174 offset:50848
	s_waitcnt lgkmcnt(8)
	v_mfma_f32_16x16x32_bf16 v[32:35], v[240:243], v[124:127], v[32:35]
	v_mfma_f32_16x16x32_bf16 v[44:47], v[240:243], v[152:155], v[44:47]
	ds_read_b64_tr_b16 v[236:237], v174 offset:46272
	ds_read_b64_tr_b16 v[238:239], v174 offset:50880
	s_waitcnt lgkmcnt(8)
	v_mfma_f32_16x16x32_bf16 v[40:43], v[244:247], v[124:127], v[40:43]
	v_mfma_f32_16x16x32_bf16 v[48:51], v[244:247], v[152:155], v[48:51]
	ds_read_b64_tr_b16 v[240:241], v174 offset:46304
	ds_read_b64_tr_b16 v[242:243], v174 offset:50912
	s_waitcnt lgkmcnt(8)
	v_mfma_f32_16x16x32_bf16 v[52:55], v[248:251], v[124:127], v[52:55]
	v_mfma_f32_16x16x32_bf16 v[60:63], v[248:251], v[152:155], v[60:63]
	ds_read_b128 v[244:247], v255 offset:0
	s_waitcnt lgkmcnt(7)
	v_mfma_f32_16x16x32_bf16 v[56:59], v[228:231], v[124:127], v[56:59]
	v_mfma_f32_16x16x32_bf16 v[68:71], v[228:231], v[152:155], v[68:71]
	ds_read_b128 v[248:251], v255 offset:64
	s_waitcnt lgkmcnt(6)
	v_mfma_f32_16x16x32_bf16 v[64:67], v[232:235], v[124:127], v[64:67]
	v_mfma_f32_16x16x32_bf16 v[76:79], v[232:235], v[152:155], v[76:79]
	ds_read_b128 v[228:231], v255 offset:4608
	s_waitcnt lgkmcnt(5)
	v_mfma_f32_16x16x32_bf16 v[72:75], v[236:239], v[124:127], v[72:75]
	v_mfma_f32_16x16x32_bf16 v[80:83], v[236:239], v[152:155], v[80:83]
	ds_read_b128 v[232:235], v255 offset:4672
	s_waitcnt lgkmcnt(4)
	v_mfma_f32_16x16x32_bf16 v[84:87], v[240:243], v[124:127], v[84:87]
	v_mfma_f32_16x16x32_bf16 v[20:23], v[240:243], v[152:155], v[20:23]
	ds_read_b128 v[236:239], v255 offset:9216
	s_waitcnt lgkmcnt(4)
	v_mfma_f32_16x16x32_bf16 v[88:91], v[244:247], v[4:7], v[156:159]
	ds_read_b128 v[240:243], v255 offset:9280
	s_waitcnt lgkmcnt(4)
	v_mfma_f32_16x16x32_bf16 v[88:91], v[248:251], v[8:11], v[88:91]
	ds_read_b128 v[244:247], v255 offset:13824
	s_waitcnt lgkmcnt(4)
	v_mfma_f32_16x16x32_bf16 v[92:95], v[228:231], v[4:7], v[160:163]
	ds_read_b128 v[248:251], v255 offset:13888
	s_waitcnt lgkmcnt(4)
	v_mfma_f32_16x16x32_bf16 v[92:95], v[232:235], v[8:11], v[92:95]
	ds_read_b128 v[228:231], v255 offset:128
	s_waitcnt lgkmcnt(4)
	v_mfma_f32_16x16x32_bf16 v[96:99], v[236:239], v[4:7], v[176:179]
	ds_read_b128 v[232:235], v255 offset:192
	s_waitcnt lgkmcnt(4)
	v_mfma_f32_16x16x32_bf16 v[96:99], v[240:243], v[8:11], v[96:99]
	ds_read_b128 v[236:239], v255 offset:4736
	s_waitcnt lgkmcnt(4)
	v_mfma_f32_16x16x32_bf16 v[100:103], v[244:247], v[4:7], v[180:183]
	ds_read_b128 v[240:243], v255 offset:4800
	s_waitcnt lgkmcnt(4)
	v_mfma_f32_16x16x32_bf16 v[100:103], v[248:251], v[8:11], v[100:103]
	ds_read_b128 v[244:247], v255 offset:9344
	s_waitcnt lgkmcnt(4)
	v_mfma_f32_16x16x32_bf16 v[104:107], v[228:231], v[12:15], v[204:207]
	ds_read_b128 v[248:251], v255 offset:9408
	s_waitcnt lgkmcnt(4)
	v_mfma_f32_16x16x32_bf16 v[104:107], v[232:235], v[16:19], v[104:107]
	ds_read_b128 v[228:231], v255 offset:13952
	s_waitcnt lgkmcnt(4)
	v_mfma_f32_16x16x32_bf16 v[108:111], v[236:239], v[12:15], v[208:211]
	ds_read_b128 v[232:235], v255 offset:14016
	s_waitcnt lgkmcnt(4)
	v_mfma_f32_16x16x32_bf16 v[108:111], v[240:243], v[16:19], v[108:111]
	s_waitcnt lgkmcnt(3)
	v_mfma_f32_16x16x32_bf16 v[112:115], v[244:247], v[12:15], v[184:187]
	s_waitcnt lgkmcnt(2)
	v_mfma_f32_16x16x32_bf16 v[112:115], v[248:251], v[16:19], v[112:115]
	s_waitcnt lgkmcnt(1)
	v_mfma_f32_16x16x32_bf16 v[116:119], v[228:231], v[12:15], v[188:191]
	s_waitcnt lgkmcnt(0)
	v_mfma_f32_16x16x32_bf16 v[116:119], v[232:235], v[16:19], v[116:119]
	v_max3_f32 v26, v88, v89, v90
	v_max3_f32 v26, v26, v91, v92
	v_max3_f32 v26, v26, v93, v94
	v_max3_f32 v26, v26, v95, v96
	v_max3_f32 v26, v26, v97, v98
	v_max3_f32 v26, v26, v99, v100
	v_max3_f32 v26, v26, v101, v102
	v_max_f32_e32 v26, v26, v103
	v_cmp_lt_f32_e32 vcc, s66, v26
	s_cbranch_vccz .Ld_nr_A0_0
	v_mov_b32_e32 v27, v26
	s_nop 1
	v_permlane16_swap_b32_e32 v26, v27
	v_max_f32_e32 v26, v26, v27
	v_mov_b32_e32 v27, v26
	s_nop 1
	v_permlane32_swap_b32_e32 v26, v27
	v_max_f32_e32 v26, v26, v27
	v_cmp_lt_f32_e32 vcc, s66, v26
	s_nop 1
	v_cndmask_b32_e32 v3, 0, v26, vcc
	v_sub_f32_e32 v2, 0, v3
	v_min_f32_e32 v2, 0, v2
	v_exp_f32_e32 v2, v2
	v_sub_f32_e32 v24, v24, v3
	v_mul_f32_e32 v0, v0, v2
	v_mul_f32_e32 v28, v28, v2
	v_mul_f32_e32 v29, v29, v2
	v_mul_f32_e32 v30, v30, v2
	v_mul_f32_e32 v31, v31, v2
	v_mul_f32_e32 v32, v32, v2
	v_mul_f32_e32 v33, v33, v2
	v_mul_f32_e32 v34, v34, v2
	v_mul_f32_e32 v35, v35, v2
	v_mul_f32_e32 v40, v40, v2
	v_mul_f32_e32 v41, v41, v2
	v_mul_f32_e32 v42, v42, v2
	v_mul_f32_e32 v43, v43, v2
	v_mul_f32_e32 v52, v52, v2
	v_mul_f32_e32 v53, v53, v2
	v_mul_f32_e32 v54, v54, v2
	v_mul_f32_e32 v55, v55, v2
	v_mul_f32_e32 v56, v56, v2
	v_mul_f32_e32 v57, v57, v2
	v_mul_f32_e32 v58, v58, v2
	v_mul_f32_e32 v59, v59, v2
	v_mul_f32_e32 v64, v64, v2
	v_mul_f32_e32 v65, v65, v2
	v_mul_f32_e32 v66, v66, v2
	v_mul_f32_e32 v67, v67, v2
	v_mul_f32_e32 v72, v72, v2
	v_mul_f32_e32 v73, v73, v2
	v_mul_f32_e32 v74, v74, v2
	v_mul_f32_e32 v75, v75, v2
	v_mul_f32_e32 v84, v84, v2
	v_mul_f32_e32 v85, v85, v2
	v_mul_f32_e32 v86, v86, v2
	v_mul_f32_e32 v87, v87, v2
	v_sub_f32_e32 v88, v88, v3
	v_sub_f32_e32 v89, v89, v3
	v_sub_f32_e32 v90, v90, v3
	v_sub_f32_e32 v91, v91, v3
	v_sub_f32_e32 v92, v92, v3
	v_sub_f32_e32 v93, v93, v3
	v_sub_f32_e32 v94, v94, v3
	v_sub_f32_e32 v95, v95, v3
	v_sub_f32_e32 v96, v96, v3
	v_sub_f32_e32 v97, v97, v3
	v_sub_f32_e32 v98, v98, v3
	v_sub_f32_e32 v99, v99, v3
	v_sub_f32_e32 v100, v100, v3
	v_sub_f32_e32 v101, v101, v3
	v_sub_f32_e32 v102, v102, v3
	v_sub_f32_e32 v103, v103, v3

.Ld_nr_A0_1:
	v_exp_f32_e32 v104, v104
	v_exp_f32_e32 v105, v105
	v_exp_f32_e32 v106, v106
	v_exp_f32_e32 v107, v107
	v_exp_f32_e32 v108, v108
	v_exp_f32_e32 v109, v109
	v_exp_f32_e32 v110, v110
	v_exp_f32_e32 v111, v111
	v_exp_f32_e32 v112, v112
	v_exp_f32_e32 v113, v113
	v_exp_f32_e32 v114, v114
	v_exp_f32_e32 v115, v115
	v_exp_f32_e32 v116, v116
	v_exp_f32_e32 v117, v117
	v_exp_f32_e32 v118, v118
	v_exp_f32_e32 v119, v119
	s_nop 0
	v_add_f32_e32 v26, v104, v105
	v_add_f32_e32 v26, v26, v106
	v_add_f32_e32 v26, v26, v107
	v_add_f32_e32 v26, v26, v108
	v_add_f32_e32 v26, v26, v109
	v_add_f32_e32 v26, v26, v110
	v_add_f32_e32 v26, v26, v111
	v_add_f32_e32 v26, v26, v112
	v_add_f32_e32 v26, v26, v113
	v_add_f32_e32 v26, v26, v114
	v_add_f32_e32 v26, v26, v115
	v_add_f32_e32 v26, v26, v116
	v_add_f32_e32 v26, v26, v117
	v_add_f32_e32 v26, v26, v118
	v_add_f32_e32 v26, v26, v119
	v_add_f32_e32 v151, v151, v26
	v_cvt_pk_bf16_f32 v128, v104, v105
	v_cvt_pk_bf16_f32 v129, v106, v107
	v_cvt_pk_bf16_f32 v130, v108, v109
	v_cvt_pk_bf16_f32 v131, v110, v111
	v_cvt_pk_bf16_f32 v152, v112, v113
	v_cvt_pk_bf16_f32 v153, v114, v115
	v_cvt_pk_bf16_f32 v154, v116, v117
	v_cvt_pk_bf16_f32 v155, v118, v119
	v_add_f32_e32 v165, 0x42800000, v165
	v_mov_b32_e32 v156, v165
	v_add_f32_e32 v157, 0x3f800000, v165
	v_add_f32_e32 v158, 0x40000000, v165
	v_add_f32_e32 v159, 0x40400000, v165
	v_add_f32_e32 v160, 0x41800000, v165
	v_add_f32_e32 v161, 0x41880000, v165
	v_add_f32_e32 v162, 0x41900000, v165
	v_add_f32_e32 v163, 0x41980000, v165
	v_add_f32_e32 v176, 0x42000000, v165
	v_add_f32_e32 v177, 0x42040000, v165
	v_add_f32_e32 v178, 0x42080000, v165
	v_add_f32_e32 v179, 0x420c0000, v165
	v_add_f32_e32 v180, 0x42400000, v165
	v_add_f32_e32 v181, 0x42440000, v165
	v_add_f32_e32 v182, 0x42480000, v165
	v_add_f32_e32 v183, 0x424c0000, v165
	v_fma_f32 v204, -v150, |v156|, v25
	v_fma_f32 v205, -v150, |v157|, v25
	v_fma_f32 v206, -v150, |v158|, v25
	v_fma_f32 v207, -v150, |v159|, v25
	v_fma_f32 v208, -v150, |v160|, v25
	v_fma_f32 v209, -v150, |v161|, v25
	v_fma_f32 v210, -v150, |v162|, v25
	v_fma_f32 v211, -v150, |v163|, v25
	v_fma_f32 v184, -v150, |v176|, v25
	v_fma_f32 v185, -v150, |v177|, v25
	v_fma_f32 v186, -v150, |v178|, v25
	v_fma_f32 v187, -v150, |v179|, v25
	v_fma_f32 v188, -v150, |v180|, v25
	v_fma_f32 v189, -v150, |v181|, v25
	v_fma_f32 v190, -v150, |v182|, v25
	v_fma_f32 v191, -v150, |v183|, v25
	v_fma_f32 v156, -v150, |v156|, v24
	v_fma_f32 v157, -v150, |v157|, v24
	v_fma_f32 v158, -v150, |v158|, v24
	v_fma_f32 v159, -v150, |v159|, v24
	v_fma_f32 v160, -v150, |v160|, v24
	v_fma_f32 v161, -v150, |v161|, v24
	v_fma_f32 v162, -v150, |v162|, v24
	v_fma_f32 v163, -v150, |v163|, v24
	v_fma_f32 v176, -v150, |v176|, v24
	v_fma_f32 v177, -v150, |v177|, v24
	v_fma_f32 v178, -v150, |v178|, v24
	v_fma_f32 v179, -v150, |v179|, v24
	v_fma_f32 v180, -v150, |v180|, v24
	v_fma_f32 v181, -v150, |v181|, v24
	v_fma_f32 v182, -v150, |v182|, v24
	v_fma_f32 v183, -v150, |v183|, v24
	s_waitcnt vmcnt(0)
	ds_write_b128 v169, v[212:215] offset:18432
	ds_write_b128 v169, v[216:219] offset:27648
	ds_write_b128 v164, v[220:223] offset:36864
	ds_write_b128 v164, v[224:227] offset:46080
	s_mov_b32 s31, s38
	s_mov_b32 s38, s39
	s_add_i32 s39, s39, 0x4800
	s_cmp_lg_u32 s39, 0xd800
	s_cselect_b32 s39, s39, 0
	s_mov_b32 s66, 0x42800000
	s_add_i32 s5, s5, 1
	s_min_u32 s8, s5, 62
	s_add_i32 s8, s8, 1
	s_mul_i32 s30, s8, 0xf8000
	v_add_u32_e32 v174, s31, v168
	v_add_u32_e32 v164, s39, v169
	s_add_u32 s80, s42, s30
	s_addc_u32 s81, s43, 0
	s_add_u32 s86, s80, 0x7c000
	s_addc_u32 s87, s81, 0
	s_add_u32 s96, s46, s30
	s_addc_u32 s97, s47, 0
	s_add_u32 s98, s96, 0x7c000
	s_addc_u32 s99, s97, 0
	s_waitcnt lgkmcnt(0)
	s_barrier
	global_load_dwordx4 v[212:215], v173, s[80:81]
	global_load_dwordx4 v[220:223], v175, s[96:97]
	global_load_dwordx4 v[216:219], v173, s[86:87]
	global_load_dwordx4 v[224:227], v175, s[98:99]
	ds_read_b64_tr_b16 v[228:229], v174 offset:36864
	ds_read_b64_tr_b16 v[230:231], v174 offset:41472
	ds_read_b64_tr_b16 v[232:233], v174 offset:36896
	ds_read_b64_tr_b16 v[234:235], v174 offset:41504
	ds_read_b64_tr_b16 v[236:237], v174 offset:36928
	ds_read_b64_tr_b16 v[238:239], v174 offset:41536
	ds_read_b64_tr_b16 v[240:241], v174 offset:36960
	ds_read_b64_tr_b16 v[242:243], v174 offset:41568
	ds_read_b64_tr_b16 v[244:245], v174 offset:36992
	ds_read_b64_tr_b16 v[246:247], v174 offset:41600
	s_waitcnt lgkmcnt(8)
	v_mfma_f32_16x16x32_bf16 v[28:31], v[228:231], v[120:123], v[28:31]
	v_mfma_f32_16x16x32_bf16 v[36:39], v[228:231], v[128:131], v[36:39]
	ds_read_b64_tr_b16 v[248:249], v174 offset:37024
	ds_read_b64_tr_b16 v[250:251], v174 offset:41632
	s_waitcnt lgkmcnt(8)
	v_mfma_f32_16x16x32_bf16 v[32:35], v[232:235], v[120:123], v[32:35]
	v_mfma_f32_16x16x32_bf16 v[44:47], v[232:235], v[128:131], v[44:47]
	ds_read_b64_tr_b16 v[228:229], v174 offset:37056
	ds_read_b64_tr_b16 v[230:231], v174 offset:41664
	s_waitcnt lgkmcnt(8)
	v_mfma_f32_16x16x32_bf16 v[40:43], v[236:239], v[120:123], v[40:43]
	v_mfma_f32_16x16x32_bf16 v[48:51], v[236:239], v[128:131], v[48:51]
	ds_read_b64_tr_b16 v[232:233], v174 offset:37088
	ds_read_b64_tr_b16 v[234:235], v174 offset:41696
	s_waitcnt lgkmcnt(8)
	v_mfma_f32_16x16x32_bf16 v[52:55], v[240:243], v[120:123], v[52:55]
	v_mfma_f32_16x16x32_bf16 v[60:63], v[240:243], v[128:131], v[60:63]
	ds_read_b64_tr_b16 v[236:237], v174 offset:46080
	ds_read_b64_tr_b16 v[238:239], v174 offset:50688
	s_waitcnt lgkmcnt(8)
	v_mfma_f32_16x16x32_bf16 v[56:59], v[244:247], v[120:123], v[56:59]
	v_mfma_f32_16x16x32_bf16 v[68:71], v[244:247], v[128:131], v[68:71]
	ds_read_b64_tr_b16 v[240:241], v174 offset:46112
	ds_read_b64_tr_b16 v[242:243], v174 offset:50720
	s_waitcnt lgkmcnt(8)
	v_mfma_f32_16x16x32_bf16 v[64:67], v[248:251], v[120:123], v[64:67]
	v_mfma_f32_16x16x32_bf16 v[76:79], v[248:251], v[128:131], v[76:79]
	ds_read_b64_tr_b16 v[244:245], v174 offset:46144
	ds_read_b64_tr_b16 v[246:247], v174 offset:50752
	s_waitcnt lgkmcnt(8)
	v_mfma_f32_16x16x32_bf16 v[72:75], v[228:231], v[120:123], v[72:75]
	v_mfma_f32_16x16x32_bf16 v[80:83], v[228:231], v[128:131], v[80:83]
	ds_read_b64_tr_b16 v[248:249], v174 offset:46176
	ds_read_b64_tr_b16 v[250:251], v174 offset:50784
	s_waitcnt lgkmcnt(8)
	v_mfma_f32_16x16x32_bf16 v[84:87], v[232:235], v[120:123], v[84:87]
	v_mfma_f32_16x16x32_bf16 v[20:23], v[232:235], v[128:131], v[20:23]
	ds_read_b64_tr_b16 v[228:229], v174 offset:46208
	ds_read_b64_tr_b16 v[230:231], v174 offset:50816
	s_waitcnt lgkmcnt(8)
	v_mfma_f32_16x16x32_bf16 v[28:31], v[236:239], v[124:127], v[28:31]
	v_mfma_f32_16x16x32_bf16 v[36:39], v[236:239], v[152:155], v[36:39]
	ds_read_b64_tr_b16 v[232:233], v174 offset:46240
	ds_read_b64_tr_b16 v[234:235], v174 offset:50848
	s_waitcnt lgkmcnt(8)
	v_mfma_f32_16x16x32_bf16 v[32:35], v[240:243], v[124:127], v[32:35]
	v_mfma_f32_16x16x32_bf16 v[44:47], v[240:243], v[152:155], v[44:47]
	ds_read_b64_tr_b16 v[236:237], v174 offset:46272
	ds_read_b64_tr_b16 v[238:239], v174 offset:50880
	s_waitcnt lgkmcnt(8)
	v_mfma_f32_16x16x32_bf16 v[40:43], v[244:247], v[124:127], v[40:43]
	v_mfma_f32_16x16x32_bf16 v[48:51], v[244:247], v[152:155], v[48:51]
	ds_read_b64_tr_b16 v[240:241], v174 offset:46304
	ds_read_b64_tr_b16 v[242:243], v174 offset:50912
	s_waitcnt lgkmcnt(8)
	v_mfma_f32_16x16x32_bf16 v[52:55], v[248:251], v[124:127], v[52:55]
	v_mfma_f32_16x16x32_bf16 v[60:63], v[248:251], v[152:155], v[60:63]
	ds_read_b128 v[244:247], v255 offset:18432
	s_waitcnt lgkmcnt(7)
	v_mfma_f32_16x16x32_bf16 v[56:59], v[228:231], v[124:127], v[56:59]
	v_mfma_f32_16x16x32_bf16 v[68:71], v[228:231], v[152:155], v[68:71]
	ds_read_b128 v[248:251], v255 offset:18496
	s_waitcnt lgkmcnt(6)
	v_mfma_f32_16x16x32_bf16 v[64:67], v[232:235], v[124:127], v[64:67]
	v_mfma_f32_16x16x32_bf16 v[76:79], v[232:235], v[152:155], v[76:79]
	ds_read_b128 v[228:231], v255 offset:23040
	s_waitcnt lgkmcnt(5)
	v_mfma_f32_16x16x32_bf16 v[72:75], v[236:239], v[124:127], v[72:75]
	v_mfma_f32_16x16x32_bf16 v[80:83], v[236:239], v[152:155], v[80:83]
	ds_read_b128 v[232:235], v255 offset:23104
	s_waitcnt lgkmcnt(4)
	v_mfma_f32_16x16x32_bf16 v[84:87], v[240:243], v[124:127], v[84:87]
	v_mfma_f32_16x16x32_bf16 v[20:23], v[240:243], v[152:155], v[20:23]
	ds_read_b128 v[236:239], v255 offset:27648
	s_waitcnt lgkmcnt(4)
	v_mfma_f32_16x16x32_bf16 v[88:91], v[244:247], v[4:7], v[156:159]
	ds_read_b128 v[240:243], v255 offset:27712
	s_waitcnt lgkmcnt(4)
	v_mfma_f32_16x16x32_bf16 v[88:91], v[248:251], v[8:11], v[88:91]
	ds_read_b128 v[244:247], v255 offset:32256
	s_waitcnt lgkmcnt(4)
	v_mfma_f32_16x16x32_bf16 v[92:95], v[228:231], v[4:7], v[160:163]
	ds_read_b128 v[248:251], v255 offset:32320
	s_waitcnt lgkmcnt(4)
	v_mfma_f32_16x16x32_bf16 v[92:95], v[232:235], v[8:11], v[92:95]
	ds_read_b128 v[228:231], v255 offset:18560
	s_waitcnt lgkmcnt(4)
	v_mfma_f32_16x16x32_bf16 v[96:99], v[236:239], v[4:7], v[176:179]
	ds_read_b128 v[232:235], v255 offset:18624
	s_waitcnt lgkmcnt(4)
	v_mfma_f32_16x16x32_bf16 v[96:99], v[240:243], v[8:11], v[96:99]
	ds_read_b128 v[236:239], v255 offset:23168
	s_waitcnt lgkmcnt(4)
	v_mfma_f32_16x16x32_bf16 v[100:103], v[244:247], v[4:7], v[180:183]
	ds_read_b128 v[240:243], v255 offset:23232
	s_waitcnt lgkmcnt(4)
	v_mfma_f32_16x16x32_bf16 v[100:103], v[248:251], v[8:11], v[100:103]
	ds_read_b128 v[244:247], v255 offset:27776
	s_waitcnt lgkmcnt(4)
	v_mfma_f32_16x16x32_bf16 v[104:107], v[228:231], v[12:15], v[204:207]
	ds_read_b128 v[248:251], v255 offset:27840
	s_waitcnt lgkmcnt(4)
	v_mfma_f32_16x16x32_bf16 v[104:107], v[232:235], v[16:19], v[104:107]
	ds_read_b128 v[228:231], v255 offset:32384
	s_waitcnt lgkmcnt(4)
	v_mfma_f32_16x16x32_bf16 v[108:111], v[236:239], v[12:15], v[208:211]
	ds_read_b128 v[232:235], v255 offset:32448
	s_waitcnt lgkmcnt(4)
	v_mfma_f32_16x16x32_bf16 v[108:111], v[240:243], v[16:19], v[108:111]
	s_waitcnt lgkmcnt(3)
	v_mfma_f32_16x16x32_bf16 v[112:115], v[244:247], v[12:15], v[184:187]
	s_waitcnt lgkmcnt(2)
	v_mfma_f32_16x16x32_bf16 v[112:115], v[248:251], v[16:19], v[112:115]
	s_waitcnt lgkmcnt(1)
	v_mfma_f32_16x16x32_bf16 v[116:119], v[228:231], v[12:15], v[188:191]
	s_waitcnt lgkmcnt(0)
	v_mfma_f32_16x16x32_bf16 v[116:119], v[232:235], v[16:19], v[116:119]
	v_max3_f32 v26, v88, v89, v90
	v_max3_f32 v26, v26, v91, v92
	v_max3_f32 v26, v26, v93, v94
	v_max3_f32 v26, v26, v95, v96
	v_max3_f32 v26, v26, v97, v98
	v_max3_f32 v26, v26, v99, v100
	v_max3_f32 v26, v26, v101, v102
	v_max_f32_e32 v26, v26, v103
	v_cmp_lt_f32_e32 vcc, s66, v26
	s_cbranch_vccz .Ld_nr_A1_0
	v_mov_b32_e32 v27, v26
	s_nop 1
	v_permlane16_swap_b32_e32 v26, v27
	v_max_f32_e32 v26, v26, v27
	v_mov_b32_e32 v27, v26
	s_nop 1
	v_permlane32_swap_b32_e32 v26, v27
	v_max_f32_e32 v26, v26, v27
	v_cmp_lt_f32_e32 vcc, s66, v26
	s_nop 1
	v_cndmask_b32_e32 v3, 0, v26, vcc
	v_sub_f32_e32 v2, 0, v3
	v_min_f32_e32 v2, 0, v2
	v_exp_f32_e32 v2, v2
	v_sub_f32_e32 v24, v24, v3
	v_mul_f32_e32 v0, v0, v2
	v_mul_f32_e32 v28, v28, v2
	v_mul_f32_e32 v29, v29, v2
	v_mul_f32_e32 v30, v30, v2
	v_mul_f32_e32 v31, v31, v2
	v_mul_f32_e32 v32, v32, v2
	v_mul_f32_e32 v33, v33, v2
	v_mul_f32_e32 v34, v34, v2
	v_mul_f32_e32 v35, v35, v2
	v_mul_f32_e32 v40, v40, v2
	v_mul_f32_e32 v41, v41, v2
	v_mul_f32_e32 v42, v42, v2
	v_mul_f32_e32 v43, v43, v2
	v_mul_f32_e32 v52, v52, v2
	v_mul_f32_e32 v53, v53, v2
	v_mul_f32_e32 v54, v54, v2
	v_mul_f32_e32 v55, v55, v2
	v_mul_f32_e32 v56, v56, v2
	v_mul_f32_e32 v57, v57, v2
	v_mul_f32_e32 v58, v58, v2
	v_mul_f32_e32 v59, v59, v2
	v_mul_f32_e32 v64, v64, v2
	v_mul_f32_e32 v65, v65, v2
	v_mul_f32_e32 v66, v66, v2
	v_mul_f32_e32 v67, v67, v2
	v_mul_f32_e32 v72, v72, v2
	v_mul_f32_e32 v73, v73, v2
	v_mul_f32_e32 v74, v74, v2
	v_mul_f32_e32 v75, v75, v2
	v_mul_f32_e32 v84, v84, v2
	v_mul_f32_e32 v85, v85, v2
	v_mul_f32_e32 v86, v86, v2
	v_mul_f32_e32 v87, v87, v2
	v_sub_f32_e32 v88, v88, v3
	v_sub_f32_e32 v89, v89, v3
	v_sub_f32_e32 v90, v90, v3
	v_sub_f32_e32 v91, v91, v3
	v_sub_f32_e32 v92, v92, v3
	v_sub_f32_e32 v93, v93, v3
	v_sub_f32_e32 v94, v94, v3
	v_sub_f32_e32 v95, v95, v3
	v_sub_f32_e32 v96, v96, v3
	v_sub_f32_e32 v97, v97, v3
	v_sub_f32_e32 v98, v98, v3
	v_sub_f32_e32 v99, v99, v3
	v_sub_f32_e32 v100, v100, v3
	v_sub_f32_e32 v101, v101, v3
	v_sub_f32_e32 v102, v102, v3
	v_sub_f32_e32 v103, v103, v3

.Ld_nr_A1_1:
	v_exp_f32_e32 v104, v104
	v_exp_f32_e32 v105, v105
	v_exp_f32_e32 v106, v106
	v_exp_f32_e32 v107, v107
	v_exp_f32_e32 v108, v108
	v_exp_f32_e32 v109, v109
	v_exp_f32_e32 v110, v110
	v_exp_f32_e32 v111, v111
	v_exp_f32_e32 v112, v112
	v_exp_f32_e32 v113, v113
	v_exp_f32_e32 v114, v114
	v_exp_f32_e32 v115, v115
	v_exp_f32_e32 v116, v116
	v_exp_f32_e32 v117, v117
	v_exp_f32_e32 v118, v118
	v_exp_f32_e32 v119, v119
	s_nop 0
	v_add_f32_e32 v26, v104, v105
	v_add_f32_e32 v26, v26, v106
	v_add_f32_e32 v26, v26, v107
	v_add_f32_e32 v26, v26, v108
	v_add_f32_e32 v26, v26, v109
	v_add_f32_e32 v26, v26, v110
	v_add_f32_e32 v26, v26, v111
	v_add_f32_e32 v26, v26, v112
	v_add_f32_e32 v26, v26, v113
	v_add_f32_e32 v26, v26, v114
	v_add_f32_e32 v26, v26, v115
	v_add_f32_e32 v26, v26, v116
	v_add_f32_e32 v26, v26, v117
	v_add_f32_e32 v26, v26, v118
	v_add_f32_e32 v26, v26, v119
	v_add_f32_e32 v151, v151, v26
	v_cvt_pk_bf16_f32 v128, v104, v105
	v_cvt_pk_bf16_f32 v129, v106, v107
	v_cvt_pk_bf16_f32 v130, v108, v109
	v_cvt_pk_bf16_f32 v131, v110, v111
	v_cvt_pk_bf16_f32 v152, v112, v113
	v_cvt_pk_bf16_f32 v153, v114, v115
	v_cvt_pk_bf16_f32 v154, v116, v117
	v_cvt_pk_bf16_f32 v155, v118, v119
	v_add_f32_e32 v165, 0x42800000, v165
	v_mov_b32_e32 v156, v165
	v_add_f32_e32 v157, 0x3f800000, v165
	v_add_f32_e32 v158, 0x40000000, v165
	v_add_f32_e32 v159, 0x40400000, v165
	v_add_f32_e32 v160, 0x41800000, v165
	v_add_f32_e32 v161, 0x41880000, v165
	v_add_f32_e32 v162, 0x41900000, v165
	v_add_f32_e32 v163, 0x41980000, v165
	v_add_f32_e32 v176, 0x42000000, v165
	v_add_f32_e32 v177, 0x42040000, v165
	v_add_f32_e32 v178, 0x42080000, v165
	v_add_f32_e32 v179, 0x420c0000, v165
	v_add_f32_e32 v180, 0x42400000, v165
	v_add_f32_e32 v181, 0x42440000, v165
	v_add_f32_e32 v182, 0x42480000, v165
	v_add_f32_e32 v183, 0x424c0000, v165
	v_fma_f32 v204, -v150, |v156|, v25
	v_fma_f32 v205, -v150, |v157|, v25
	v_fma_f32 v206, -v150, |v158|, v25
	v_fma_f32 v207, -v150, |v159|, v25
	v_fma_f32 v208, -v150, |v160|, v25
	v_fma_f32 v209, -v150, |v161|, v25
	v_fma_f32 v210, -v150, |v162|, v25
	v_fma_f32 v211, -v150, |v163|, v25
	v_fma_f32 v184, -v150, |v176|, v25
	v_fma_f32 v185, -v150, |v177|, v25
	v_fma_f32 v186, -v150, |v178|, v25
	v_fma_f32 v187, -v150, |v179|, v25
	v_fma_f32 v188, -v150, |v180|, v25
	v_fma_f32 v189, -v150, |v181|, v25
	v_fma_f32 v190, -v150, |v182|, v25
	v_fma_f32 v191, -v150, |v183|, v25
	v_fma_f32 v156, -v150, |v156|, v24
	v_fma_f32 v157, -v150, |v157|, v24
	v_fma_f32 v158, -v150, |v158|, v24
	v_fma_f32 v159, -v150, |v159|, v24
	v_fma_f32 v160, -v150, |v160|, v24
	v_fma_f32 v161, -v150, |v161|, v24
	v_fma_f32 v162, -v150, |v162|, v24
	v_fma_f32 v163, -v150, |v163|, v24
	v_fma_f32 v176, -v150, |v176|, v24
	v_fma_f32 v177, -v150, |v177|, v24
	v_fma_f32 v178, -v150, |v178|, v24
	v_fma_f32 v179, -v150, |v179|, v24
	v_fma_f32 v180, -v150, |v180|, v24
	v_fma_f32 v181, -v150, |v181|, v24
	v_fma_f32 v182, -v150, |v182|, v24
	v_fma_f32 v183, -v150, |v183|, v24
	s_waitcnt vmcnt(0)
	ds_write_b128 v169, v[212:215] offset:0
	ds_write_b128 v169, v[216:219] offset:9216
	ds_write_b128 v164, v[220:223] offset:36864
	ds_write_b128 v164, v[224:227] offset:46080
	s_mov_b32 s31, s38
	s_mov_b32 s38, s39
	s_add_i32 s39, s39, 0x4800
	s_cmp_lg_u32 s39, 0xd800
	s_cselect_b32 s39, s39, 0
	s_mov_b32 s66, 0x42800000
	s_add_i32 s5, s5, 1
	s_min_u32 s8, s5, 62
	s_add_i32 s8, s8, 1
	s_mul_i32 s30, s8, 0xf8000
	v_add_u32_e32 v174, s31, v168
	v_add_u32_e32 v164, s39, v169
	s_add_u32 s80, s42, s30
	s_addc_u32 s81, s43, 0
	s_add_u32 s86, s80, 0x7c000
	s_addc_u32 s87, s81, 0
	s_add_u32 s96, s46, s30
	s_addc_u32 s97, s47, 0
	s_add_u32 s98, s96, 0x7c000
	s_addc_u32 s99, s97, 0
	s_waitcnt lgkmcnt(0)
	s_barrier
	s_cmp_lt_u32 s5, 64
	s_cbranch_scc1 .Ld_loopA
	v_add_u32_e32 v174, s31, v168
	ds_read_b64_tr_b16 v[228:229], v174 offset:36864
	ds_read_b64_tr_b16 v[230:231], v174 offset:41472
	ds_read_b64_tr_b16 v[232:233], v174 offset:36896
	ds_read_b64_tr_b16 v[234:235], v174 offset:41504
	ds_read_b64_tr_b16 v[236:237], v174 offset:36928
	ds_read_b64_tr_b16 v[238:239], v174 offset:41536
	ds_read_b64_tr_b16 v[240:241], v174 offset:36960
	ds_read_b64_tr_b16 v[242:243], v174 offset:41568
	ds_read_b64_tr_b16 v[244:245], v174 offset:36992
	ds_read_b64_tr_b16 v[246:247], v174 offset:41600
	s_waitcnt lgkmcnt(8)
	v_mfma_f32_16x16x32_bf16 v[28:31], v[228:231], v[120:123], v[28:31]
	v_mfma_f32_16x16x32_bf16 v[36:39], v[228:231], v[128:131], v[36:39]
	ds_read_b64_tr_b16 v[248:249], v174 offset:37024
	ds_read_b64_tr_b16 v[250:251], v174 offset:41632
	s_waitcnt lgkmcnt(8)
	v_mfma_f32_16x16x32_bf16 v[32:35], v[232:235], v[120:123], v[32:35]
	v_mfma_f32_16x16x32_bf16 v[44:47], v[232:235], v[128:131], v[44:47]
	ds_read_b64_tr_b16 v[228:229], v174 offset:37056
	ds_read_b64_tr_b16 v[230:231], v174 offset:41664
	s_waitcnt lgkmcnt(8)
	v_mfma_f32_16x16x32_bf16 v[40:43], v[236:239], v[120:123], v[40:43]
	v_mfma_f32_16x16x32_bf16 v[48:51], v[236:239], v[128:131], v[48:51]
	ds_read_b64_tr_b16 v[232:233], v174 offset:37088
	ds_read_b64_tr_b16 v[234:235], v174 offset:41696
	s_waitcnt lgkmcnt(8)
	v_mfma_f32_16x16x32_bf16 v[52:55], v[240:243], v[120:123], v[52:55]
	v_mfma_f32_16x16x32_bf16 v[60:63], v[240:243], v[128:131], v[60:63]
	ds_read_b64_tr_b16 v[236:237], v174 offset:46080
	ds_read_b64_tr_b16 v[238:239], v174 offset:50688
	s_waitcnt lgkmcnt(8)
	v_mfma_f32_16x16x32_bf16 v[56:59], v[244:247], v[120:123], v[56:59]
	v_mfma_f32_16x16x32_bf16 v[68:71], v[244:247], v[128:131], v[68:71]
	ds_read_b64_tr_b16 v[240:241], v174 offset:46112
	ds_read_b64_tr_b16 v[242:243], v174 offset:50720
	s_waitcnt lgkmcnt(8)
	v_mfma_f32_16x16x32_bf16 v[64:67], v[248:251], v[120:123], v[64:67]
	v_mfma_f32_16x16x32_bf16 v[76:79], v[248:251], v[128:131], v[76:79]
	ds_read_b64_tr_b16 v[244:245], v174 offset:46144
	ds_read_b64_tr_b16 v[246:247], v174 offset:50752
	s_waitcnt lgkmcnt(8)
	v_mfma_f32_16x16x32_bf16 v[72:75], v[228:231], v[120:123], v[72:75]
	v_mfma_f32_16x16x32_bf16 v[80:83], v[228:231], v[128:131], v[80:83]
	ds_read_b64_tr_b16 v[248:249], v174 offset:46176
	ds_read_b64_tr_b16 v[250:251], v174 offset:50784
	s_waitcnt lgkmcnt(8)
	v_mfma_f32_16x16x32_bf16 v[84:87], v[232:235], v[120:123], v[84:87]
	v_mfma_f32_16x16x32_bf16 v[20:23], v[232:235], v[128:131], v[20:23]
	ds_read_b64_tr_b16 v[228:229], v174 offset:46208
	ds_read_b64_tr_b16 v[230:231], v174 offset:50816
	s_waitcnt lgkmcnt(8)
	v_mfma_f32_16x16x32_bf16 v[28:31], v[236:239], v[124:127], v[28:31]
	v_mfma_f32_16x16x32_bf16 v[36:39], v[236:239], v[152:155], v[36:39]
	ds_read_b64_tr_b16 v[232:233], v174 offset:46240
	ds_read_b64_tr_b16 v[234:235], v174 offset:50848
	s_waitcnt lgkmcnt(8)
	v_mfma_f32_16x16x32_bf16 v[32:35], v[240:243], v[124:127], v[32:35]
	v_mfma_f32_16x16x32_bf16 v[44:47], v[240:243], v[152:155], v[44:47]
	ds_read_b64_tr_b16 v[236:237], v174 offset:46272
	ds_read_b64_tr_b16 v[238:239], v174 offset:50880
	s_waitcnt lgkmcnt(8)
	v_mfma_f32_16x16x32_bf16 v[40:43], v[244:247], v[124:127], v[40:43]
	v_mfma_f32_16x16x32_bf16 v[48:51], v[244:247], v[152:155], v[48:51]
	ds_read_b64_tr_b16 v[240:241], v174 offset:46304
	ds_read_b64_tr_b16 v[242:243], v174 offset:50912
	s_waitcnt lgkmcnt(8)
	v_mfma_f32_16x16x32_bf16 v[52:55], v[248:251], v[124:127], v[52:55]
	v_mfma_f32_16x16x32_bf16 v[60:63], v[248:251], v[152:155], v[60:63]
	s_waitcnt lgkmcnt(6)
	v_mfma_f32_16x16x32_bf16 v[56:59], v[228:231], v[124:127], v[56:59]
	v_mfma_f32_16x16x32_bf16 v[68:71], v[228:231], v[152:155], v[68:71]
	s_waitcnt lgkmcnt(4)
	v_mfma_f32_16x16x32_bf16 v[64:67], v[232:235], v[124:127], v[64:67]
	v_mfma_f32_16x16x32_bf16 v[76:79], v[232:235], v[152:155], v[76:79]
	s_waitcnt lgkmcnt(2)
	v_mfma_f32_16x16x32_bf16 v[72:75], v[236:239], v[124:127], v[72:75]
	v_mfma_f32_16x16x32_bf16 v[80:83], v[236:239], v[152:155], v[80:83]
	s_waitcnt lgkmcnt(0)
	v_mfma_f32_16x16x32_bf16 v[84:87], v[240:243], v[124:127], v[84:87]
	v_mfma_f32_16x16x32_bf16 v[20:23], v[240:243], v[152:155], v[20:23]

.LBB0_641:
	s_ashr_i32 s0, s5, 7
	s_mul_i32 s23, s0, 0x3e00000
	s_mul_hi_i32 s17, s0, 0x3e00000
	s_add_u32 s0, s2, s23
	s_addc_u32 s1, s4, s17
	s_lshl_b32 s8, s5, 8
	s_and_b32 s8, s8, 0xf00
	v_and_b32_e32 v32, 15, v2
	v_lshl_add_u32 v0, v0, 5, s8
	s_waitcnt lgkmcnt(0)
	v_or_b32_e32 v3, v0, v32
	v_mov_b64_e32 v[4:5], s[0:1]
	v_mad_i64_i32 v[6:7], s[0:1], v3, s65, v[4:5]
	s_lshl_b32 s0, s5, 3
	v_or_b32_e32 v3, 16, v3
	s_and_b32 s8, s0, 0x380
	v_mad_i64_i32 v[8:9], s[0:1], v3, s65, v[4:5]
	v_ashrrev_i32_e32 v3, 3, v2
	s_waitcnt lgkmcnt(0)
	v_bfe_u32 v33, v2, 4, 2
	v_lshl_add_u64 v[6:7], v[6:7], 0, s[8:9]
	s_mov_b64 s[12:13], 0x1000
	v_lshl_add_u64 v[8:9], v[8:9], 0, s[8:9]
	v_mad_i64_i32 v[4:5], s[0:1], v3, s65, v[4:5]
	v_lshl_add_u64 v[110:111], v[6:7], 0, s[12:13]
	v_lshlrev_b32_e32 v0, 4, v33
	v_lshl_add_u64 v[108:109], v[8:9], 0, s[12:13]
	s_and_b32 s0, s5, 64
	v_lshl_add_u64 v[6:7], v[110:111], 0, v[0:1]
	v_lshl_add_u64 v[28:29], v[108:109], 0, v[0:1]
	s_lshl_b32 s8, s0, 1
	v_lshlrev_b32_e32 v0, 4, v2
	v_and_b32_e32 v0, 0x70, v0
	v_lshl_add_u64 v[4:5], v[4:5], 0, s[8:9]
	v_lshl_add_u64 v[30:31], v[4:5], 0, v[0:1]
	v_add_co_u32_e32 v4, vcc, s71, v30
	v_lshlrev_b32_e32 v118, 2, v33
	s_nop 0
	v_addc_co_u32_e32 v5, vcc, 0, v31, vcc
	global_load_dwordx4 v[20:23], v[4:5], off offset:1024
	global_load_dwordx4 v[24:27], v[4:5], off offset:1280
	global_load_dwordx4 v[16:19], v[6:7], off
	global_load_dwordx4 v[8:11], v[6:7], off offset:64
	global_load_dwordx4 v[12:15], v[28:29], off
	s_nop 0
	global_load_dwordx4 v[4:7], v[28:29], off offset:64
	v_bfe_u32 v29, v2, 2, 2
	v_lshlrev_b32_e32 v28, 3, v2
	v_or_b32_e32 v29, v118, v29
	s_mov_b64 s[18:19], 0x1400
	v_lshlrev_b32_e32 v34, 3, v33
	v_mul_lo_u32 v35, v3, s40
	v_mul_u32_u24_e32 v32, 0x50, v32
	v_and_b32_e32 v28, 24, v28
	v_mul_u32_u24_e32 v29, 0xa0, v29
	v_lshl_add_u64 v[112:113], v[30:31], 0, s[18:19]
	s_mov_b64 s[18:19], 0x1500
	s_mov_b64 s[88:89], 0x1000
	s_mov_b64 s[0:1], -1
	v_lshlrev_b32_e32 v116, 1, v32
	v_add3_u32 v119, 0, v29, v28
	s_cmp_lt_i32 s30, 4
	v_add3_u32 v120, 0, v35, v0
	v_lshl_add_u64 v[114:115], v[30:31], 0, s[18:19]
	v_lshlrev_b32_e32 v0, 1, v34
	s_barrier
	s_waitcnt vmcnt(5)
	ds_write_b128 v120, v[20:23]
	s_waitcnt vmcnt(4)
	ds_write_b128 v120, v[24:27] offset:20480
	s_waitcnt lgkmcnt(0)
	s_barrier
	s_cbranch_scc1 .Lb_groupA
	s_waitcnt vmcnt(0)
	v_mov_b32_e32 v34, 0
	v_mov_b32_e32 v35, 0
	v_mov_b32_e32 v36, 0
	v_mov_b32_e32 v37, 0
	v_mov_b32_e32 v42, 0
	v_mov_b32_e32 v43, 0
	v_mov_b32_e32 v44, 0
	v_mov_b32_e32 v45, 0
	v_mov_b32_e32 v56, 0
	v_mov_b32_e32 v57, 0
	v_mov_b32_e32 v58, 0
	v_mov_b32_e32 v59, 0
	v_mov_b32_e32 v60, 0
	v_mov_b32_e32 v61, 0
	v_mov_b32_e32 v62, 0
	v_mov_b32_e32 v63, 0
	v_mov_b32_e32 v20, 0
	v_mov_b32_e32 v21, 0
	v_mov_b32_e32 v22, 0
	v_mov_b32_e32 v23, 0
	v_mov_b32_e32 v24, 0
	v_mov_b32_e32 v25, 0
	v_mov_b32_e32 v26, 0
	v_mov_b32_e32 v27, 0
	v_mov_b32_e32 v38, 0
	v_mov_b32_e32 v39, 0
	v_mov_b32_e32 v40, 0
	v_mov_b32_e32 v41, 0
	v_mov_b32_e32 v28, 0
	v_mov_b32_e32 v29, 0
	v_mov_b32_e32 v30, 0
	v_mov_b32_e32 v31, 0
	v_mov_b32_e32 v180, 0
	v_mov_b32_e32 v181, 0
	v_mov_b32_e32 v182, 0
	v_mov_b32_e32 v183, 0
	v_mov_b32_e32 v184, 0
	v_mov_b32_e32 v185, 0
	v_mov_b32_e32 v186, 0
	v_mov_b32_e32 v187, 0
	v_mov_b32_e32 v188, 0
	v_mov_b32_e32 v189, 0
	v_mov_b32_e32 v190, 0
	v_mov_b32_e32 v191, 0
	v_mov_b32_e32 v204, 0
	v_mov_b32_e32 v205, 0
	v_mov_b32_e32 v206, 0
	v_mov_b32_e32 v207, 0
	v_mov_b32_e32 v48, 0
	v_mov_b32_e32 v49, 0
	v_mov_b32_e32 v50, 0
	v_mov_b32_e32 v51, 0
	v_mov_b32_e32 v52, 0
	v_mov_b32_e32 v53, 0
	v_mov_b32_e32 v54, 0
	v_mov_b32_e32 v55, 0
	v_mov_b32_e32 v80, 0
	v_mov_b32_e32 v64, 0
	v_add_u32_e32 v75, v116, v0
	v_readfirstlane_b32 s80, v112
	v_readfirstlane_b32 s81, v113
	v_readfirstlane_b32 s86, v114
	v_readfirstlane_b32 s87, v115
	s_nop 3
	v_subrev_u32_e32 v71, s80, v112
	v_subrev_u32_e32 v73, s86, v114
	s_mov_b32 s20, 0
	s_mov_b32 s42, 0
	s_mov_b32 s43, 0
	s_mov_b32 s51, 10240
	s_mov_b32 s30, 0xf8000
	s_mov_b32 s66, 0xff800000
	s_mov_b32 s67, 0xff800000
	v_add_u32_e32 v72, s42, v119
	v_add_u32_e32 v74, s51, v120
	s_add_u32 s96, s80, s30
	s_addc_u32 s97, s81, 0
	s_add_u32 s98, s86, s30
	s_addc_u32 s99, s87, 0
	v_mov_b32_e32 v88, 0xff800000
	v_mov_b32_e32 v89, 0xff800000
	v_mov_b32_e32 v90, 0xff800000
	v_mov_b32_e32 v91, 0xff800000
	v_mov_b32_e32 v92, 0xff800000
	v_mov_b32_e32 v93, 0xff800000
	v_mov_b32_e32 v94, 0xff800000
	v_mov_b32_e32 v95, 0xff800000
	v_mov_b32_e32 v96, 0xff800000
	v_mov_b32_e32 v97, 0xff800000
	v_mov_b32_e32 v98, 0xff800000
	v_mov_b32_e32 v99, 0xff800000
	v_mov_b32_e32 v100, 0xff800000
	v_mov_b32_e32 v101, 0xff800000
	v_mov_b32_e32 v102, 0xff800000
	v_mov_b32_e32 v103, 0xff800000
	v_mov_b32_e32 v104, 0xff800000
	v_mov_b32_e32 v105, 0xff800000
	v_mov_b32_e32 v106, 0xff800000
	v_mov_b32_e32 v107, 0xff800000
	v_mov_b32_e32 v168, 0xff800000
	v_mov_b32_e32 v169, 0xff800000
	v_mov_b32_e32 v170, 0xff800000
	v_mov_b32_e32 v171, 0xff800000
	v_mov_b32_e32 v172, 0xff800000
	v_mov_b32_e32 v173, 0xff800000
	v_mov_b32_e32 v174, 0xff800000
	v_mov_b32_e32 v175, 0xff800000
	v_mov_b32_e32 v176, 0xff800000
	v_mov_b32_e32 v177, 0xff800000
	v_mov_b32_e32 v178, 0xff800000
	v_mov_b32_e32 v179, 0xff800000
.Lb_loopB:
	global_load_dwordx4 v[208:211], v71, s[96:97]
	global_load_dwordx4 v[212:215], v73, s[98:99]
	ds_read_b128 v[216:219], v75 offset:0
	ds_read_b128 v[220:223], v75 offset:64
	ds_read_b128 v[224:227], v75 offset:2560
	ds_read_b128 v[228:231], v75 offset:2624
	v_exp_f32_e32 v236, v88
	v_exp_f32_e32 v237, v89
	v_exp_f32_e32 v238, v90
	v_exp_f32_e32 v239, v91
	v_exp_f32_e32 v240, v92
	v_exp_f32_e32 v241, v93
	v_exp_f32_e32 v242, v94
	v_exp_f32_e32 v243, v95
	v_exp_f32_e32 v244, v96
	v_exp_f32_e32 v245, v97
	v_exp_f32_e32 v246, v98
	v_exp_f32_e32 v247, v99
	v_exp_f32_e32 v248, v100
	v_exp_f32_e32 v249, v101
	v_exp_f32_e32 v250, v102
	v_exp_f32_e32 v251, v103
	s_nop 0
	v_add_f32_e32 v67, v236, v237
	v_add_f32_e32 v67, v67, v238
	v_add_f32_e32 v67, v67, v239
	v_add_f32_e32 v67, v67, v240
	v_add_f32_e32 v67, v67, v241
	v_add_f32_e32 v67, v67, v242
	v_add_f32_e32 v67, v67, v243
	v_add_f32_e32 v67, v67, v244
	v_add_f32_e32 v67, v67, v245
	v_add_f32_e32 v67, v67, v246
	v_add_f32_e32 v67, v67, v247
	v_add_f32_e32 v67, v67, v248
	v_add_f32_e32 v67, v67, v249
	v_add_f32_e32 v67, v67, v250
	v_add_f32_e32 v67, v67, v251
	v_cmp_lt_f32_e32 vcc, s66, v67
	s_cbranch_vccnz .Lb_rare_B0_0

.Lb_back_B0_1:
	v_add_f32_e32 v64, v64, v67
	v_cvt_pk_bf16_f32 v184, v236, v237
	v_cvt_pk_bf16_f32 v185, v238, v239
	v_cvt_pk_bf16_f32 v186, v240, v241
	v_cvt_pk_bf16_f32 v187, v242, v243
	v_cvt_pk_bf16_f32 v204, v244, v245
	v_cvt_pk_bf16_f32 v205, v246, v247
	v_cvt_pk_bf16_f32 v206, v248, v249
	v_cvt_pk_bf16_f32 v207, v250, v251
	ds_read_b128 v[232:235], v75 offset:5120
	s_waitcnt lgkmcnt(4)
	v_mfma_f32_16x16x32_bf16 v[88:91], v[216:219], v[16:19], v[48:51]
	v_mfma_f32_16x16x32_bf16 v[104:107], v[216:219], v[12:15], v[52:55]
	ds_read_b128 v[216:219], v75 offset:5184
	s_waitcnt lgkmcnt(4)
	v_mfma_f32_16x16x32_bf16 v[88:91], v[220:223], v[8:11], v[88:91]
	v_mfma_f32_16x16x32_bf16 v[104:107], v[220:223], v[4:7], v[104:107]
	ds_read_b128 v[220:223], v75 offset:7680
	s_waitcnt lgkmcnt(4)
	v_mfma_f32_16x16x32_bf16 v[92:95], v[224:227], v[16:19], v[48:51]
	v_mfma_f32_16x16x32_bf16 v[168:171], v[224:227], v[12:15], v[52:55]
	ds_read_b128 v[224:227], v75 offset:7744
	s_waitcnt lgkmcnt(4)
	v_mfma_f32_16x16x32_bf16 v[92:95], v[228:231], v[8:11], v[92:95]
	v_mfma_f32_16x16x32_bf16 v[168:171], v[228:231], v[4:7], v[168:171]
	ds_read_b64_tr_b16 v[228:229], v72 offset:20480
	ds_read_b64_tr_b16 v[230:231], v72 offset:23040
	s_waitcnt lgkmcnt(5)
	v_mfma_f32_16x16x32_bf16 v[96:99], v[232:235], v[16:19], v[48:51]
	v_mfma_f32_16x16x32_bf16 v[172:175], v[232:235], v[12:15], v[52:55]
	ds_read_b64_tr_b16 v[232:233], v72 offset:20512
	ds_read_b64_tr_b16 v[234:235], v72 offset:23072
	s_waitcnt lgkmcnt(6)
	v_mfma_f32_16x16x32_bf16 v[96:99], v[216:219], v[8:11], v[96:99]
	v_mfma_f32_16x16x32_bf16 v[172:175], v[216:219], v[4:7], v[172:175]
	ds_read_b64_tr_b16 v[216:217], v72 offset:20544
	ds_read_b64_tr_b16 v[218:219], v72 offset:23104
	s_waitcnt lgkmcnt(7)
	v_mfma_f32_16x16x32_bf16 v[100:103], v[220:223], v[16:19], v[48:51]
	v_mfma_f32_16x16x32_bf16 v[176:179], v[220:223], v[12:15], v[52:55]
	ds_read_b64_tr_b16 v[220:221], v72 offset:20576
	ds_read_b64_tr_b16 v[222:223], v72 offset:23136
	s_waitcnt lgkmcnt(8)
	v_mfma_f32_16x16x32_bf16 v[100:103], v[224:227], v[8:11], v[100:103]
	v_mfma_f32_16x16x32_bf16 v[176:179], v[224:227], v[4:7], v[176:179]
	ds_read_b64_tr_b16 v[224:225], v72 offset:25600
	ds_read_b64_tr_b16 v[226:227], v72 offset:28160
	s_waitcnt lgkmcnt(8)
	v_mfma_f32_16x16x32_bf16 v[34:37], v[228:231], v[180:183], v[34:37]
	v_mfma_f32_16x16x32_bf16 v[20:23], v[228:231], v[184:187], v[20:23]
	ds_read_b64_tr_b16 v[228:229], v72 offset:25632
	ds_read_b64_tr_b16 v[230:231], v72 offset:28192
	s_waitcnt lgkmcnt(8)
	v_mfma_f32_16x16x32_bf16 v[42:45], v[232:235], v[180:183], v[42:45]
	v_mfma_f32_16x16x32_bf16 v[24:27], v[232:235], v[184:187], v[24:27]
	ds_read_b64_tr_b16 v[232:233], v72 offset:25664
	ds_read_b64_tr_b16 v[234:235], v72 offset:28224
	s_waitcnt lgkmcnt(8)
	v_mfma_f32_16x16x32_bf16 v[56:59], v[216:219], v[180:183], v[56:59]
	v_mfma_f32_16x16x32_bf16 v[38:41], v[216:219], v[184:187], v[38:41]
	ds_read_b64_tr_b16 v[216:217], v72 offset:25696
	ds_read_b64_tr_b16 v[218:219], v72 offset:28256
	s_waitcnt lgkmcnt(8)
	v_mfma_f32_16x16x32_bf16 v[60:63], v[220:223], v[180:183], v[60:63]
	v_mfma_f32_16x16x32_bf16 v[28:31], v[220:223], v[184:187], v[28:31]
	s_waitcnt lgkmcnt(6)
	v_mfma_f32_16x16x32_bf16 v[34:37], v[224:227], v[188:191], v[34:37]
	v_mfma_f32_16x16x32_bf16 v[20:23], v[224:227], v[204:207], v[20:23]
	s_waitcnt lgkmcnt(4)
	v_mfma_f32_16x16x32_bf16 v[42:45], v[228:231], v[188:191], v[42:45]
	v_mfma_f32_16x16x32_bf16 v[24:27], v[228:231], v[204:207], v[24:27]
	s_waitcnt lgkmcnt(2)
	v_mfma_f32_16x16x32_bf16 v[56:59], v[232:235], v[188:191], v[56:59]
	v_mfma_f32_16x16x32_bf16 v[38:41], v[232:235], v[204:207], v[38:41]
	s_waitcnt lgkmcnt(0)
	v_mfma_f32_16x16x32_bf16 v[60:63], v[216:219], v[188:191], v[60:63]
	v_mfma_f32_16x16x32_bf16 v[28:31], v[216:219], v[204:207], v[28:31]
	s_mov_b32 s42, s43
	s_mov_b32 s43, s51
	s_add_i32 s51, s51, 10240
	s_cmp_lg_u32 s51, 30720
	s_cselect_b32 s51, s51, 0
	s_min_u32 s8, s20, 61
	s_add_i32 s8, s8, 2
	s_mul_i32 s30, s8, 0xf8000
	s_nop 1
	s_waitcnt vmcnt(0)
	ds_write_b128 v120, v[208:211] offset:10240
	ds_write_b128 v74, v[212:215] offset:20480
	s_mov_b32 s66, 0xff800000
	s_mov_b32 s67, 0xff800000
	s_cmp_ge_u32 s20, 1
	s_cselect_b32 s66, 0x5f800000, s66
	s_cselect_b32 s67, 0x42000000, s67
	s_add_i32 s20, s20, 1
	v_add_u32_e32 v72, s42, v119
	v_add_u32_e32 v74, s51, v120
	s_add_u32 s96, s80, s30
	s_addc_u32 s97, s81, 0
	s_add_u32 s98, s86, s30
	s_addc_u32 s99, s87, 0
	s_waitcnt lgkmcnt(0)
	s_barrier
	global_load_dwordx4 v[208:211], v71, s[96:97]
	global_load_dwordx4 v[212:215], v73, s[98:99]
	ds_read_b128 v[216:219], v75 offset:10240
	ds_read_b128 v[220:223], v75 offset:10304
	ds_read_b128 v[224:227], v75 offset:12800
	ds_read_b128 v[228:231], v75 offset:12864
	v_exp_f32_e32 v236, v88
	v_exp_f32_e32 v237, v89
	v_exp_f32_e32 v238, v90
	v_exp_f32_e32 v239, v91
	v_exp_f32_e32 v240, v92
	v_exp_f32_e32 v241, v93
	v_exp_f32_e32 v242, v94
	v_exp_f32_e32 v243, v95
	v_exp_f32_e32 v244, v96
	v_exp_f32_e32 v245, v97
	v_exp_f32_e32 v246, v98
	v_exp_f32_e32 v247, v99
	v_exp_f32_e32 v248, v100
	v_exp_f32_e32 v249, v101
	v_exp_f32_e32 v250, v102
	v_exp_f32_e32 v251, v103
	s_nop 0
	v_add_f32_e32 v67, v236, v237
	v_add_f32_e32 v67, v67, v238
	v_add_f32_e32 v67, v67, v239
	v_add_f32_e32 v67, v67, v240
	v_add_f32_e32 v67, v67, v241
	v_add_f32_e32 v67, v67, v242
	v_add_f32_e32 v67, v67, v243
	v_add_f32_e32 v67, v67, v244
	v_add_f32_e32 v67, v67, v245
	v_add_f32_e32 v67, v67, v246
	v_add_f32_e32 v67, v67, v247
	v_add_f32_e32 v67, v67, v248
	v_add_f32_e32 v67, v67, v249
	v_add_f32_e32 v67, v67, v250
	v_add_f32_e32 v67, v67, v251
	v_cmp_lt_f32_e32 vcc, s66, v67
	s_cbranch_vccnz .Lb_rare_B1_0

.Lb_back_B1_1:
	v_add_f32_e32 v64, v64, v67
	v_cvt_pk_bf16_f32 v184, v236, v237
	v_cvt_pk_bf16_f32 v185, v238, v239
	v_cvt_pk_bf16_f32 v186, v240, v241
	v_cvt_pk_bf16_f32 v187, v242, v243
	v_cvt_pk_bf16_f32 v204, v244, v245
	v_cvt_pk_bf16_f32 v205, v246, v247
	v_cvt_pk_bf16_f32 v206, v248, v249
	v_cvt_pk_bf16_f32 v207, v250, v251
	ds_read_b128 v[232:235], v75 offset:15360
	s_waitcnt lgkmcnt(4)
	v_mfma_f32_16x16x32_bf16 v[88:91], v[216:219], v[16:19], v[48:51]
	v_mfma_f32_16x16x32_bf16 v[104:107], v[216:219], v[12:15], v[52:55]
	ds_read_b128 v[216:219], v75 offset:15424
	s_waitcnt lgkmcnt(4)
	v_mfma_f32_16x16x32_bf16 v[88:91], v[220:223], v[8:11], v[88:91]
	v_mfma_f32_16x16x32_bf16 v[104:107], v[220:223], v[4:7], v[104:107]
	ds_read_b128 v[220:223], v75 offset:17920
	s_waitcnt lgkmcnt(4)
	v_mfma_f32_16x16x32_bf16 v[92:95], v[224:227], v[16:19], v[48:51]
	v_mfma_f32_16x16x32_bf16 v[168:171], v[224:227], v[12:15], v[52:55]
	ds_read_b128 v[224:227], v75 offset:17984
	s_waitcnt lgkmcnt(4)
	v_mfma_f32_16x16x32_bf16 v[92:95], v[228:231], v[8:11], v[92:95]
	v_mfma_f32_16x16x32_bf16 v[168:171], v[228:231], v[4:7], v[168:171]
	ds_read_b64_tr_b16 v[228:229], v72 offset:20480
	ds_read_b64_tr_b16 v[230:231], v72 offset:23040
	s_waitcnt lgkmcnt(5)
	v_mfma_f32_16x16x32_bf16 v[96:99], v[232:235], v[16:19], v[48:51]
	v_mfma_f32_16x16x32_bf16 v[172:175], v[232:235], v[12:15], v[52:55]
	ds_read_b64_tr_b16 v[232:233], v72 offset:20512
	ds_read_b64_tr_b16 v[234:235], v72 offset:23072
	s_waitcnt lgkmcnt(6)
	v_mfma_f32_16x16x32_bf16 v[96:99], v[216:219], v[8:11], v[96:99]
	v_mfma_f32_16x16x32_bf16 v[172:175], v[216:219], v[4:7], v[172:175]
	ds_read_b64_tr_b16 v[216:217], v72 offset:20544
	ds_read_b64_tr_b16 v[218:219], v72 offset:23104
	s_waitcnt lgkmcnt(7)
	v_mfma_f32_16x16x32_bf16 v[100:103], v[220:223], v[16:19], v[48:51]
	v_mfma_f32_16x16x32_bf16 v[176:179], v[220:223], v[12:15], v[52:55]
	ds_read_b64_tr_b16 v[220:221], v72 offset:20576
	ds_read_b64_tr_b16 v[222:223], v72 offset:23136
	s_waitcnt lgkmcnt(8)
	v_mfma_f32_16x16x32_bf16 v[100:103], v[224:227], v[8:11], v[100:103]
	v_mfma_f32_16x16x32_bf16 v[176:179], v[224:227], v[4:7], v[176:179]
	ds_read_b64_tr_b16 v[224:225], v72 offset:25600
	ds_read_b64_tr_b16 v[226:227], v72 offset:28160
	s_waitcnt lgkmcnt(8)
	v_mfma_f32_16x16x32_bf16 v[34:37], v[228:231], v[180:183], v[34:37]
	v_mfma_f32_16x16x32_bf16 v[20:23], v[228:231], v[184:187], v[20:23]
	ds_read_b64_tr_b16 v[228:229], v72 offset:25632
	ds_read_b64_tr_b16 v[230:231], v72 offset:28192
	s_waitcnt lgkmcnt(8)
	v_mfma_f32_16x16x32_bf16 v[42:45], v[232:235], v[180:183], v[42:45]
	v_mfma_f32_16x16x32_bf16 v[24:27], v[232:235], v[184:187], v[24:27]
	ds_read_b64_tr_b16 v[232:233], v72 offset:25664
	ds_read_b64_tr_b16 v[234:235], v72 offset:28224
	s_waitcnt lgkmcnt(8)
	v_mfma_f32_16x16x32_bf16 v[56:59], v[216:219], v[180:183], v[56:59]
	v_mfma_f32_16x16x32_bf16 v[38:41], v[216:219], v[184:187], v[38:41]
	ds_read_b64_tr_b16 v[216:217], v72 offset:25696
	ds_read_b64_tr_b16 v[218:219], v72 offset:28256
	s_waitcnt lgkmcnt(8)
	v_mfma_f32_16x16x32_bf16 v[60:63], v[220:223], v[180:183], v[60:63]
	v_mfma_f32_16x16x32_bf16 v[28:31], v[220:223], v[184:187], v[28:31]
	s_waitcnt lgkmcnt(6)
	v_mfma_f32_16x16x32_bf16 v[34:37], v[224:227], v[188:191], v[34:37]
	v_mfma_f32_16x16x32_bf16 v[20:23], v[224:227], v[204:207], v[20:23]
	s_waitcnt lgkmcnt(4)
	v_mfma_f32_16x16x32_bf16 v[42:45], v[228:231], v[188:191], v[42:45]
	v_mfma_f32_16x16x32_bf16 v[24:27], v[228:231], v[204:207], v[24:27]
	s_waitcnt lgkmcnt(2)
	v_mfma_f32_16x16x32_bf16 v[56:59], v[232:235], v[188:191], v[56:59]
	v_mfma_f32_16x16x32_bf16 v[38:41], v[232:235], v[204:207], v[38:41]
	s_waitcnt lgkmcnt(0)
	v_mfma_f32_16x16x32_bf16 v[60:63], v[216:219], v[188:191], v[60:63]
	v_mfma_f32_16x16x32_bf16 v[28:31], v[216:219], v[204:207], v[28:31]
	s_mov_b32 s42, s43
	s_mov_b32 s43, s51
	s_add_i32 s51, s51, 10240
	s_cmp_lg_u32 s51, 30720
	s_cselect_b32 s51, s51, 0
	s_min_u32 s8, s20, 61
	s_add_i32 s8, s8, 2
	s_mul_i32 s30, s8, 0xf8000
	s_nop 1
	s_waitcnt vmcnt(0)
	ds_write_b128 v120, v[208:211] offset:0
	ds_write_b128 v74, v[212:215] offset:20480
	s_mov_b32 s66, 0xff800000
	s_mov_b32 s67, 0xff800000
	s_cmp_ge_u32 s20, 1
	s_cselect_b32 s66, 0x5f800000, s66
	s_cselect_b32 s67, 0x42000000, s67
	s_add_i32 s20, s20, 1
	v_add_u32_e32 v72, s42, v119
	v_add_u32_e32 v74, s51, v120
	s_add_u32 s96, s80, s30
	s_addc_u32 s97, s81, 0
	s_add_u32 s98, s86, s30
	s_addc_u32 s99, s87, 0
	s_waitcnt lgkmcnt(0)
	s_barrier
	s_cmp_lt_u32 s20, 64
	s_cbranch_scc1 .Lb_loopB
	v_add_u32_e32 v72, s42, v119
	ds_read_b64_tr_b16 v[216:217], v72 offset:20480
	ds_read_b64_tr_b16 v[218:219], v72 offset:23040
	ds_read_b64_tr_b16 v[220:221], v72 offset:20512
	ds_read_b64_tr_b16 v[222:223], v72 offset:23072
	ds_read_b64_tr_b16 v[224:225], v72 offset:20544
	ds_read_b64_tr_b16 v[226:227], v72 offset:23104
	ds_read_b64_tr_b16 v[228:229], v72 offset:20576
	ds_read_b64_tr_b16 v[230:231], v72 offset:23136
	v_exp_f32_e32 v236, v88
	v_exp_f32_e32 v237, v89
	v_exp_f32_e32 v238, v90
	v_exp_f32_e32 v239, v91
	v_exp_f32_e32 v240, v92
	v_exp_f32_e32 v241, v93
	v_exp_f32_e32 v242, v94
	v_exp_f32_e32 v243, v95
	v_exp_f32_e32 v244, v96
	v_exp_f32_e32 v245, v97
	v_exp_f32_e32 v246, v98
	v_exp_f32_e32 v247, v99
	v_exp_f32_e32 v248, v100
	v_exp_f32_e32 v249, v101
	v_exp_f32_e32 v250, v102
	v_exp_f32_e32 v251, v103
	s_nop 0
	v_add_f32_e32 v67, v236, v237
	v_add_f32_e32 v67, v67, v238
	v_add_f32_e32 v67, v67, v239
	v_add_f32_e32 v67, v67, v240
	v_add_f32_e32 v67, v67, v241
	v_add_f32_e32 v67, v67, v242
	v_add_f32_e32 v67, v67, v243
	v_add_f32_e32 v67, v67, v244
	v_add_f32_e32 v67, v67, v245
	v_add_f32_e32 v67, v67, v246
	v_add_f32_e32 v67, v67, v247
	v_add_f32_e32 v67, v67, v248
	v_add_f32_e32 v67, v67, v249
	v_add_f32_e32 v67, v67, v250
	v_add_f32_e32 v67, v67, v251
	v_cmp_lt_f32_e32 vcc, s66, v67
	s_cbranch_vccnz .Lb_rare_Bt_0

.Lb_groupA:
	s_waitcnt vmcnt(0)
	v_mov_b32_e32 v34, 0
	v_mov_b32_e32 v35, 0
	v_mov_b32_e32 v36, 0
	v_mov_b32_e32 v37, 0
	v_mov_b32_e32 v42, 0
	v_mov_b32_e32 v43, 0
	v_mov_b32_e32 v44, 0
	v_mov_b32_e32 v45, 0
	v_mov_b32_e32 v56, 0
	v_mov_b32_e32 v57, 0
	v_mov_b32_e32 v58, 0
	v_mov_b32_e32 v59, 0
	v_mov_b32_e32 v60, 0
	v_mov_b32_e32 v61, 0
	v_mov_b32_e32 v62, 0
	v_mov_b32_e32 v63, 0
	v_mov_b32_e32 v20, 0
	v_mov_b32_e32 v21, 0
	v_mov_b32_e32 v22, 0
	v_mov_b32_e32 v23, 0
	v_mov_b32_e32 v24, 0
	v_mov_b32_e32 v25, 0
	v_mov_b32_e32 v26, 0
	v_mov_b32_e32 v27, 0
	v_mov_b32_e32 v38, 0
	v_mov_b32_e32 v39, 0
	v_mov_b32_e32 v40, 0
	v_mov_b32_e32 v41, 0
	v_mov_b32_e32 v28, 0
	v_mov_b32_e32 v29, 0
	v_mov_b32_e32 v30, 0
	v_mov_b32_e32 v31, 0
	v_mov_b32_e32 v180, 0
	v_mov_b32_e32 v181, 0
	v_mov_b32_e32 v182, 0
	v_mov_b32_e32 v183, 0
	v_mov_b32_e32 v184, 0
	v_mov_b32_e32 v185, 0
	v_mov_b32_e32 v186, 0
	v_mov_b32_e32 v187, 0
	v_mov_b32_e32 v188, 0
	v_mov_b32_e32 v189, 0
	v_mov_b32_e32 v190, 0
	v_mov_b32_e32 v191, 0
	v_mov_b32_e32 v204, 0
	v_mov_b32_e32 v205, 0
	v_mov_b32_e32 v206, 0
	v_mov_b32_e32 v207, 0
	v_mov_b32_e32 v48, 0
	v_mov_b32_e32 v49, 0
	v_mov_b32_e32 v50, 0
	v_mov_b32_e32 v51, 0
	v_mov_b32_e32 v52, 0
	v_mov_b32_e32 v53, 0
	v_mov_b32_e32 v54, 0
	v_mov_b32_e32 v55, 0
	v_mov_b32_e32 v80, 0
	v_mov_b32_e32 v64, 0
	v_add_u32_e32 v75, v116, v0
	v_readfirstlane_b32 s80, v112
	v_readfirstlane_b32 s81, v113
	v_readfirstlane_b32 s86, v114
	v_readfirstlane_b32 s87, v115
	s_nop 3
	v_subrev_u32_e32 v71, s80, v112
	v_subrev_u32_e32 v73, s86, v114
	s_mov_b32 s20, 0
	s_mov_b32 s42, 0
	s_mov_b32 s43, 0
	s_mov_b32 s51, 10240
	s_mov_b32 s30, 0xf8000
	s_mov_b32 s66, 0xff800000
	s_mov_b32 s67, 0xff800000
	v_add_u32_e32 v72, s42, v119
	v_add_u32_e32 v74, s51, v120
	s_add_u32 s96, s80, s30
	s_addc_u32 s97, s81, 0
	s_add_u32 s98, s86, s30
	s_addc_u32 s99, s87, 0
.Lb_loopA:
	global_load_dwordx4 v[208:211], v71, s[96:97]
	global_load_dwordx4 v[212:215], v73, s[98:99]
	ds_read_b64_tr_b16 v[216:217], v72 offset:20480
	ds_read_b64_tr_b16 v[218:219], v72 offset:23040
	ds_read_b64_tr_b16 v[220:221], v72 offset:20512
	ds_read_b64_tr_b16 v[222:223], v72 offset:23072
	ds_read_b64_tr_b16 v[224:225], v72 offset:20544
	ds_read_b64_tr_b16 v[226:227], v72 offset:23104
	ds_read_b64_tr_b16 v[228:229], v72 offset:20576
	ds_read_b64_tr_b16 v[230:231], v72 offset:23136
	ds_read_b64_tr_b16 v[232:233], v72 offset:25600
	ds_read_b64_tr_b16 v[234:235], v72 offset:28160
	s_waitcnt lgkmcnt(8)
	v_mfma_f32_16x16x32_bf16 v[34:37], v[216:219], v[180:183], v[34:37]
	v_mfma_f32_16x16x32_bf16 v[20:23], v[216:219], v[184:187], v[20:23]
	ds_read_b64_tr_b16 v[216:217], v72 offset:25632
	ds_read_b64_tr_b16 v[218:219], v72 offset:28192
	s_waitcnt lgkmcnt(8)
	v_mfma_f32_16x16x32_bf16 v[42:45], v[220:223], v[180:183], v[42:45]
	v_mfma_f32_16x16x32_bf16 v[24:27], v[220:223], v[184:187], v[24:27]
	ds_read_b64_tr_b16 v[220:221], v72 offset:25664
	ds_read_b64_tr_b16 v[222:223], v72 offset:28224
	s_waitcnt lgkmcnt(8)
	v_mfma_f32_16x16x32_bf16 v[56:59], v[224:227], v[180:183], v[56:59]
	v_mfma_f32_16x16x32_bf16 v[38:41], v[224:227], v[184:187], v[38:41]
	ds_read_b64_tr_b16 v[224:225], v72 offset:25696
	ds_read_b64_tr_b16 v[226:227], v72 offset:28256
	s_waitcnt lgkmcnt(8)
	v_mfma_f32_16x16x32_bf16 v[60:63], v[228:231], v[180:183], v[60:63]
	v_mfma_f32_16x16x32_bf16 v[28:31], v[228:231], v[184:187], v[28:31]
	ds_read_b128 v[228:231], v75 offset:0
	s_waitcnt lgkmcnt(7)
	v_mfma_f32_16x16x32_bf16 v[34:37], v[232:235], v[188:191], v[34:37]
	v_mfma_f32_16x16x32_bf16 v[20:23], v[232:235], v[204:207], v[20:23]
	ds_read_b128 v[232:235], v75 offset:64
	s_waitcnt lgkmcnt(6)
	v_mfma_f32_16x16x32_bf16 v[42:45], v[216:219], v[188:191], v[42:45]
	v_mfma_f32_16x16x32_bf16 v[24:27], v[216:219], v[204:207], v[24:27]
	ds_read_b128 v[216:219], v75 offset:2560
	s_waitcnt lgkmcnt(5)
	v_mfma_f32_16x16x32_bf16 v[56:59], v[220:223], v[188:191], v[56:59]
	v_mfma_f32_16x16x32_bf16 v[38:41], v[220:223], v[204:207], v[38:41]
	ds_read_b128 v[220:223], v75 offset:2624
	s_waitcnt lgkmcnt(4)
	v_mfma_f32_16x16x32_bf16 v[60:63], v[224:227], v[188:191], v[60:63]
	v_mfma_f32_16x16x32_bf16 v[28:31], v[224:227], v[204:207], v[28:31]
	ds_read_b128 v[224:227], v75 offset:5120
	s_waitcnt lgkmcnt(4)
	v_mfma_f32_16x16x32_bf16 v[88:91], v[228:231], v[16:19], v[48:51]
	v_mfma_f32_16x16x32_bf16 v[104:107], v[228:231], v[12:15], v[52:55]
	ds_read_b128 v[228:231], v75 offset:5184
	s_waitcnt lgkmcnt(4)
	v_mfma_f32_16x16x32_bf16 v[88:91], v[232:235], v[8:11], v[88:91]
	v_mfma_f32_16x16x32_bf16 v[104:107], v[232:235], v[4:7], v[104:107]
	ds_read_b128 v[232:235], v75 offset:7680
	s_waitcnt lgkmcnt(4)
	v_mfma_f32_16x16x32_bf16 v[92:95], v[216:219], v[16:19], v[48:51]
	v_mfma_f32_16x16x32_bf16 v[168:171], v[216:219], v[12:15], v[52:55]
	ds_read_b128 v[216:219], v75 offset:7744
	s_waitcnt lgkmcnt(4)
	v_mfma_f32_16x16x32_bf16 v[92:95], v[220:223], v[8:11], v[92:95]
	v_mfma_f32_16x16x32_bf16 v[168:171], v[220:223], v[4:7], v[168:171]
	s_waitcnt lgkmcnt(3)
	v_mfma_f32_16x16x32_bf16 v[96:99], v[224:227], v[16:19], v[48:51]
	v_mfma_f32_16x16x32_bf16 v[172:175], v[224:227], v[12:15], v[52:55]
	s_waitcnt lgkmcnt(2)
	v_mfma_f32_16x16x32_bf16 v[96:99], v[228:231], v[8:11], v[96:99]
	v_mfma_f32_16x16x32_bf16 v[172:175], v[228:231], v[4:7], v[172:175]
	s_waitcnt lgkmcnt(1)
	v_mfma_f32_16x16x32_bf16 v[100:103], v[232:235], v[16:19], v[48:51]
	v_mfma_f32_16x16x32_bf16 v[176:179], v[232:235], v[12:15], v[52:55]
	s_waitcnt lgkmcnt(0)
	v_mfma_f32_16x16x32_bf16 v[100:103], v[216:219], v[8:11], v[100:103]
	v_mfma_f32_16x16x32_bf16 v[176:179], v[216:219], v[4:7], v[176:179]
	s_mov_b32 s42, s43
	s_mov_b32 s43, s51
	s_add_i32 s51, s51, 10240
	s_cmp_lg_u32 s51, 30720
	s_cselect_b32 s51, s51, 0
	s_min_u32 s8, s20, 61
	s_add_i32 s8, s8, 2
	s_mul_i32 s30, s8, 0xf8000
	s_nop 1
	v_exp_f32_e32 v236, v88
	v_exp_f32_e32 v237, v89
	v_exp_f32_e32 v238, v90
	v_exp_f32_e32 v239, v91
	v_exp_f32_e32 v240, v92
	v_exp_f32_e32 v241, v93
	v_exp_f32_e32 v242, v94
	v_exp_f32_e32 v243, v95
	v_exp_f32_e32 v244, v96
	v_exp_f32_e32 v245, v97
	v_exp_f32_e32 v246, v98
	v_exp_f32_e32 v247, v99
	v_exp_f32_e32 v248, v100
	v_exp_f32_e32 v249, v101
	v_exp_f32_e32 v250, v102
	v_exp_f32_e32 v251, v103
	s_nop 0
	v_add_f32_e32 v67, v236, v237
	v_add_f32_e32 v67, v67, v238
	v_add_f32_e32 v67, v67, v239
	v_add_f32_e32 v67, v67, v240
	v_add_f32_e32 v67, v67, v241
	v_add_f32_e32 v67, v67, v242
	v_add_f32_e32 v67, v67, v243
	v_add_f32_e32 v67, v67, v244
	v_add_f32_e32 v67, v67, v245
	v_add_f32_e32 v67, v67, v246
	v_add_f32_e32 v67, v67, v247
	v_add_f32_e32 v67, v67, v248
	v_add_f32_e32 v67, v67, v249
	v_add_f32_e32 v67, v67, v250
	v_add_f32_e32 v67, v67, v251
	v_cmp_lt_f32_e32 vcc, s66, v67
	s_cbranch_vccnz .Lb_rare_A0_0

.Lb_back_A0_1:
	v_add_f32_e32 v64, v64, v67
	v_cvt_pk_bf16_f32 v184, v236, v237
	v_cvt_pk_bf16_f32 v185, v238, v239
	v_cvt_pk_bf16_f32 v186, v240, v241
	v_cvt_pk_bf16_f32 v187, v242, v243
	v_cvt_pk_bf16_f32 v204, v244, v245
	v_cvt_pk_bf16_f32 v205, v246, v247
	v_cvt_pk_bf16_f32 v206, v248, v249
	v_cvt_pk_bf16_f32 v207, v250, v251
	s_waitcnt vmcnt(0)
	ds_write_b128 v120, v[208:211] offset:10240
	ds_write_b128 v74, v[212:215] offset:20480
	s_mov_b32 s66, 0x5f800000
	s_mov_b32 s67, 0x42000000
	s_add_i32 s20, s20, 1
	v_add_u32_e32 v72, s42, v119
	v_add_u32_e32 v74, s51, v120
	s_add_u32 s96, s80, s30
	s_addc_u32 s97, s81, 0
	s_add_u32 s98, s86, s30
	s_addc_u32 s99, s87, 0
	s_waitcnt lgkmcnt(0)
	s_barrier
	global_load_dwordx4 v[208:211], v71, s[96:97]
	global_load_dwordx4 v[212:215], v73, s[98:99]
	ds_read_b64_tr_b16 v[216:217], v72 offset:20480
	ds_read_b64_tr_b16 v[218:219], v72 offset:23040
	ds_read_b64_tr_b16 v[220:221], v72 offset:20512
	ds_read_b64_tr_b16 v[222:223], v72 offset:23072
	ds_read_b64_tr_b16 v[224:225], v72 offset:20544
	ds_read_b64_tr_b16 v[226:227], v72 offset:23104
	ds_read_b64_tr_b16 v[228:229], v72 offset:20576
	ds_read_b64_tr_b16 v[230:231], v72 offset:23136
	ds_read_b64_tr_b16 v[232:233], v72 offset:25600
	ds_read_b64_tr_b16 v[234:235], v72 offset:28160
	s_waitcnt lgkmcnt(8)
	v_mfma_f32_16x16x32_bf16 v[34:37], v[216:219], v[180:183], v[34:37]
	v_mfma_f32_16x16x32_bf16 v[20:23], v[216:219], v[184:187], v[20:23]
	ds_read_b64_tr_b16 v[216:217], v72 offset:25632
	ds_read_b64_tr_b16 v[218:219], v72 offset:28192
	s_waitcnt lgkmcnt(8)
	v_mfma_f32_16x16x32_bf16 v[42:45], v[220:223], v[180:183], v[42:45]
	v_mfma_f32_16x16x32_bf16 v[24:27], v[220:223], v[184:187], v[24:27]
	ds_read_b64_tr_b16 v[220:221], v72 offset:25664
	ds_read_b64_tr_b16 v[222:223], v72 offset:28224
	s_waitcnt lgkmcnt(8)
	v_mfma_f32_16x16x32_bf16 v[56:59], v[224:227], v[180:183], v[56:59]
	v_mfma_f32_16x16x32_bf16 v[38:41], v[224:227], v[184:187], v[38:41]
	ds_read_b64_tr_b16 v[224:225], v72 offset:25696
	ds_read_b64_tr_b16 v[226:227], v72 offset:28256
	s_waitcnt lgkmcnt(8)
	v_mfma_f32_16x16x32_bf16 v[60:63], v[228:231], v[180:183], v[60:63]
	v_mfma_f32_16x16x32_bf16 v[28:31], v[228:231], v[184:187], v[28:31]
	ds_read_b128 v[228:231], v75 offset:10240
	s_waitcnt lgkmcnt(7)
	v_mfma_f32_16x16x32_bf16 v[34:37], v[232:235], v[188:191], v[34:37]
	v_mfma_f32_16x16x32_bf16 v[20:23], v[232:235], v[204:207], v[20:23]
	ds_read_b128 v[232:235], v75 offset:10304
	s_waitcnt lgkmcnt(6)
	v_mfma_f32_16x16x32_bf16 v[42:45], v[216:219], v[188:191], v[42:45]
	v_mfma_f32_16x16x32_bf16 v[24:27], v[216:219], v[204:207], v[24:27]
	ds_read_b128 v[216:219], v75 offset:12800
	s_waitcnt lgkmcnt(5)
	v_mfma_f32_16x16x32_bf16 v[56:59], v[220:223], v[188:191], v[56:59]
	v_mfma_f32_16x16x32_bf16 v[38:41], v[220:223], v[204:207], v[38:41]
	ds_read_b128 v[220:223], v75 offset:12864
	s_waitcnt lgkmcnt(4)
	v_mfma_f32_16x16x32_bf16 v[60:63], v[224:227], v[188:191], v[60:63]
	v_mfma_f32_16x16x32_bf16 v[28:31], v[224:227], v[204:207], v[28:31]
	ds_read_b128 v[224:227], v75 offset:15360
	s_waitcnt lgkmcnt(4)
	v_mfma_f32_16x16x32_bf16 v[88:91], v[228:231], v[16:19], v[48:51]
	v_mfma_f32_16x16x32_bf16 v[104:107], v[228:231], v[12:15], v[52:55]
	ds_read_b128 v[228:231], v75 offset:15424
	s_waitcnt lgkmcnt(4)
	v_mfma_f32_16x16x32_bf16 v[88:91], v[232:235], v[8:11], v[88:91]
	v_mfma_f32_16x16x32_bf16 v[104:107], v[232:235], v[4:7], v[104:107]
	ds_read_b128 v[232:235], v75 offset:17920
	s_waitcnt lgkmcnt(4)
	v_mfma_f32_16x16x32_bf16 v[92:95], v[216:219], v[16:19], v[48:51]
	v_mfma_f32_16x16x32_bf16 v[168:171], v[216:219], v[12:15], v[52:55]
	ds_read_b128 v[216:219], v75 offset:17984
	s_waitcnt lgkmcnt(4)
	v_mfma_f32_16x16x32_bf16 v[92:95], v[220:223], v[8:11], v[92:95]
	v_mfma_f32_16x16x32_bf16 v[168:171], v[220:223], v[4:7], v[168:171]
	s_waitcnt lgkmcnt(3)
	v_mfma_f32_16x16x32_bf16 v[96:99], v[224:227], v[16:19], v[48:51]
	v_mfma_f32_16x16x32_bf16 v[172:175], v[224:227], v[12:15], v[52:55]
	s_waitcnt lgkmcnt(2)
	v_mfma_f32_16x16x32_bf16 v[96:99], v[228:231], v[8:11], v[96:99]
	v_mfma_f32_16x16x32_bf16 v[172:175], v[228:231], v[4:7], v[172:175]
	s_waitcnt lgkmcnt(1)
	v_mfma_f32_16x16x32_bf16 v[100:103], v[232:235], v[16:19], v[48:51]
	v_mfma_f32_16x16x32_bf16 v[176:179], v[232:235], v[12:15], v[52:55]
	s_waitcnt lgkmcnt(0)
	v_mfma_f32_16x16x32_bf16 v[100:103], v[216:219], v[8:11], v[100:103]
	v_mfma_f32_16x16x32_bf16 v[176:179], v[216:219], v[4:7], v[176:179]
	s_mov_b32 s42, s43
	s_mov_b32 s43, s51
	s_add_i32 s51, s51, 10240
	s_cmp_lg_u32 s51, 30720
	s_cselect_b32 s51, s51, 0
	s_min_u32 s8, s20, 61
	s_add_i32 s8, s8, 2
	s_mul_i32 s30, s8, 0xf8000
	s_nop 1
	v_exp_f32_e32 v236, v88
	v_exp_f32_e32 v237, v89
	v_exp_f32_e32 v238, v90
	v_exp_f32_e32 v239, v91
	v_exp_f32_e32 v240, v92
	v_exp_f32_e32 v241, v93
	v_exp_f32_e32 v242, v94
	v_exp_f32_e32 v243, v95
	v_exp_f32_e32 v244, v96
	v_exp_f32_e32 v245, v97
	v_exp_f32_e32 v246, v98
	v_exp_f32_e32 v247, v99
	v_exp_f32_e32 v248, v100
	v_exp_f32_e32 v249, v101
	v_exp_f32_e32 v250, v102
	v_exp_f32_e32 v251, v103
	s_nop 0
	v_add_f32_e32 v67, v236, v237
	v_add_f32_e32 v67, v67, v238
	v_add_f32_e32 v67, v67, v239
	v_add_f32_e32 v67, v67, v240
	v_add_f32_e32 v67, v67, v241
	v_add_f32_e32 v67, v67, v242
	v_add_f32_e32 v67, v67, v243
	v_add_f32_e32 v67, v67, v244
	v_add_f32_e32 v67, v67, v245
	v_add_f32_e32 v67, v67, v246
	v_add_f32_e32 v67, v67, v247
	v_add_f32_e32 v67, v67, v248
	v_add_f32_e32 v67, v67, v249
	v_add_f32_e32 v67, v67, v250
	v_add_f32_e32 v67, v67, v251
	v_cmp_lt_f32_e32 vcc, s66, v67
	s_cbranch_vccnz .Lb_rare_A1_0

.Lb_back_A1_1:
	v_add_f32_e32 v64, v64, v67
	v_cvt_pk_bf16_f32 v184, v236, v237
	v_cvt_pk_bf16_f32 v185, v238, v239
	v_cvt_pk_bf16_f32 v186, v240, v241
	v_cvt_pk_bf16_f32 v187, v242, v243
	v_cvt_pk_bf16_f32 v204, v244, v245
	v_cvt_pk_bf16_f32 v205, v246, v247
	v_cvt_pk_bf16_f32 v206, v248, v249
	v_cvt_pk_bf16_f32 v207, v250, v251
	s_waitcnt vmcnt(0)
	ds_write_b128 v120, v[208:211] offset:0
	ds_write_b128 v74, v[212:215] offset:20480
	s_mov_b32 s66, 0x5f800000
	s_mov_b32 s67, 0x42000000
	s_add_i32 s20, s20, 1
	v_add_u32_e32 v72, s42, v119
	v_add_u32_e32 v74, s51, v120
	s_add_u32 s96, s80, s30
	s_addc_u32 s97, s81, 0
	s_add_u32 s98, s86, s30
	s_addc_u32 s99, s87, 0
	s_waitcnt lgkmcnt(0)
	s_barrier
	s_cmp_lt_u32 s20, 64
	s_cbranch_scc1 .Lb_loopA
	v_add_u32_e32 v72, s42, v119
	ds_read_b64_tr_b16 v[216:217], v72 offset:20480
	ds_read_b64_tr_b16 v[218:219], v72 offset:23040
	ds_read_b64_tr_b16 v[220:221], v72 offset:20512
	ds_read_b64_tr_b16 v[222:223], v72 offset:23072
	ds_read_b64_tr_b16 v[224:225], v72 offset:20544
	ds_read_b64_tr_b16 v[226:227], v72 offset:23104
	ds_read_b64_tr_b16 v[228:229], v72 offset:20576
	ds_read_b64_tr_b16 v[230:231], v72 offset:23136
	ds_read_b64_tr_b16 v[232:233], v72 offset:25600
	ds_read_b64_tr_b16 v[234:235], v72 offset:28160
	s_waitcnt lgkmcnt(8)
	v_mfma_f32_16x16x32_bf16 v[34:37], v[216:219], v[180:183], v[34:37]
	v_mfma_f32_16x16x32_bf16 v[20:23], v[216:219], v[184:187], v[20:23]
	ds_read_b64_tr_b16 v[216:217], v72 offset:25632
	ds_read_b64_tr_b16 v[218:219], v72 offset:28192
	s_waitcnt lgkmcnt(8)
	v_mfma_f32_16x16x32_bf16 v[42:45], v[220:223], v[180:183], v[42:45]
	v_mfma_f32_16x16x32_bf16 v[24:27], v[220:223], v[184:187], v[24:27]
	ds_read_b64_tr_b16 v[220:221], v72 offset:25664
	ds_read_b64_tr_b16 v[222:223], v72 offset:28224
	s_waitcnt lgkmcnt(8)
	v_mfma_f32_16x16x32_bf16 v[56:59], v[224:227], v[180:183], v[56:59]
	v_mfma_f32_16x16x32_bf16 v[38:41], v[224:227], v[184:187], v[38:41]
	ds_read_b64_tr_b16 v[224:225], v72 offset:25696
	ds_read_b64_tr_b16 v[226:227], v72 offset:28256
	s_waitcnt lgkmcnt(8)
	v_mfma_f32_16x16x32_bf16 v[60:63], v[228:231], v[180:183], v[60:63]
	v_mfma_f32_16x16x32_bf16 v[28:31], v[228:231], v[184:187], v[28:31]
	s_waitcnt lgkmcnt(6)
	v_mfma_f32_16x16x32_bf16 v[34:37], v[232:235], v[188:191], v[34:37]
	v_mfma_f32_16x16x32_bf16 v[20:23], v[232:235], v[204:207], v[20:23]
	s_waitcnt lgkmcnt(4)
	v_mfma_f32_16x16x32_bf16 v[42:45], v[216:219], v[188:191], v[42:45]
	v_mfma_f32_16x16x32_bf16 v[24:27], v[216:219], v[204:207], v[24:27]
	s_waitcnt lgkmcnt(2)
	v_mfma_f32_16x16x32_bf16 v[56:59], v[220:223], v[188:191], v[56:59]
	v_mfma_f32_16x16x32_bf16 v[38:41], v[220:223], v[204:207], v[38:41]
	s_waitcnt lgkmcnt(0)
	v_mfma_f32_16x16x32_bf16 v[60:63], v[224:227], v[188:191], v[60:63]
	v_mfma_f32_16x16x32_bf16 v[28:31], v[224:227], v[204:207], v[28:31]
